# attention bias-table staging loop unrolled, both loads issued before the first wait; on top of the all-changes combination
# speedup vs baseline: 1.0012x; 1.0001x over previous
; #define LAS __attribute__((address_space(3)))
; __device__ __forceinline__ void attn_item(const bf16_t* Z, const float* ck, const float* cv, const float* btab, const float* sinks, bf16_t* MIX, int item, LAS unsigned char* lds, int tid, int wave, int lane) {
;     ...
;     for (int i = tid; i < 1024; i += NTHR) bts[i] = btab[(kvh * 4 + (i >> 8)) * 256 + (i & 255)];
;     const int c16 = lane & 15, g = lane >> 4, gh = wave >> 1, qhalf = wave & 1, hq = kvh * 4 + gh;
;     bf16x8 Qf[2][4];
; #pragma unroll
;     for (int nb = 0; nb < 2; ++nb)
; #pragma unroll
;         for (int kk = 0; kk < 4; ++kk) Qf[nb][kk] = *(const bf16x8*)(Z + (size_t)(qrow0 + qhalf * 32 + nb * 16 + c16) * DIN + ZQ + hq * 128 + 32 * kk + 8 * g);
;     const float sink = sinks[hq];
;     __syncthreads();
;     f32x4 sacc[12][2];
; #pragma unroll
;     for (int mb = 0; mb < 12; ++mb) { sacc[mb][0] = (f32x4){0.f, 0.f, 0.f, 0.f}; sacc[mb][1] = (f32x4){0.f, 0.f, 0.f, 0.f};
; #pragma unroll
;         for (int kk = 0; kk < 4; ++kk) { const bf16x8 Kf = *(const LAS bf16x8*)(Ks + (16 * mb + c16) * KS_STRIDE + 32 * kk + 8 * g);
;             sacc[mb][0] = __builtin_amdgcn_mfma_f32_16x16x32_bf16(Kf, Qf[0][kk], sacc[mb][0], 0, 0, 0);
;             sacc[mb][1] = __builtin_amdgcn_mfma_f32_16x16x32_bf16(Kf, Qf[1][kk], sacc[mb][1], 0, 0, 0); } }
.LBB0_642:
	global_load_dword v4, v[0:1], off
	v_lshl_add_u64 v[0:1], v[0:1], 0, s[86:87]
	global_load_dword v5, v[0:1], off
	s_waitcnt vmcnt(1)
	ds_write_b32 v3, v4
	s_waitcnt vmcnt(0)
	ds_write_b32 v3, v5 offset:2048
	s_or_b64 exec, exec, s[6:7]
	s_lshl_b32 s6, s14, 2
	v_readlane_b32 s7, v236, 37
	s_add_i32 s8, s6, s7
	v_and_b32_e32 v149, 15, v125
	v_readlane_b32 s6, v236, 36
	s_lshl_b32 s76, s8, 8
	v_and_b32_e32 v122, -16, v125
	v_or_b32_e32 v126, s6, v149
	s_add_u32 s6, s68, s76
	s_addc_u32 s7, s69, 0
	v_mov_b32_e32 v123, v121
	v_add_u32_e32 v6, s20, v126
	v_lshl_add_u64 v[4:5], s[6:7], 0, v[122:123]
	v_mad_u64_u32 v[0:1], s[6:7], v6, s74, v[4:5]
	v_add_u32_e32 v6, 16, v6
	v_mad_u64_u32 v[4:5], s[6:7], v6, s74, v[4:5]
	global_load_dwordx4 v[76:79], v[0:1], off
	global_load_dwordx4 v[64:67], v[0:1], off offset:64
	global_load_dwordx4 v[56:59], v[0:1], off offset:128
	s_nop 0
	global_load_dwordx4 v[0:3], v[0:1], off offset:192
	s_nop 0
	global_load_dwordx4 v[84:87], v[4:5], off
	global_load_dwordx4 v[80:83], v[4:5], off offset:64
	global_load_dwordx4 v[68:71], v[4:5], off offset:128
	global_load_dwordx4 v[60:63], v[4:5], off offset:192
	s_lshl_b32 s6, s8, 2
	v_mov_b32_e32 v4, s6
	s_load_dwordx2 s[6:7], s[42:43], 0x88
	s_movk_i32 s8, 0x110
	v_or_b32_e32 v146, 0x70, v125
	v_or_b32_e32 v148, 48, v125
	v_or_b32_e32 v123, 0xb0, v125
	s_waitcnt lgkmcnt(0)
	global_load_dword v150, v4, s[6:7]
	v_and_b32_e32 v4, 48, v125
	v_add_u32_e32 v124, 0, v4
	v_mad_u32_u24 v44, v149, s8, v124
	s_barrier
	ds_read_b128 v[4:7], v44
	ds_read_b128 v[12:15], v44 offset:64
	v_mad_u64_u32 v[46:47], s[6:7], v146, s8, v[124:125]
	v_mad_u64_u32 v[28:29], s[6:7], v148, s8, v[124:125]
	v_lshrrev_b32_e32 v127, 4, v125
	v_mad_u64_u32 v[124:125], s[6:7], v123, s8, v[124:125]
	v_writelane_b32 v236, s20, 54
	v_lshlrev_b32_e32 v120, 3, v127
	v_readlane_b32 s6, v236, 38
	v_or_b32_e32 v147, 64, v149
	s_waitcnt vmcnt(8) lgkmcnt(1)
	v_mfma_f32_16x16x32_bf16 v[8:11], v[4:7], v[76:79], 0
	ds_read_b128 v[16:19], v44 offset:4416
	ds_read_b128 v[20:23], v44 offset:8768
	ds_read_b128 v[32:35], v44 offset:21824
	s_waitcnt vmcnt(4)
	v_mfma_f32_16x16x32_bf16 v[4:7], v[4:7], v[84:87], 0
	ds_read_b128 v[36:39], v44 offset:26176
	ds_read_b128 v[40:43], v46 offset:64
	ds_read_b128 v[24:27], v28 offset:64
	s_waitcnt lgkmcnt(6)
	v_mfma_f32_16x16x32_bf16 v[8:11], v[12:15], v[64:67], v[8:11]
	ds_read_b128 v[108:111], v44 offset:34880
	ds_read_b128 v[112:115], v44 offset:35008
	ds_read_b128 v[116:119], v44 offset:39232
	s_waitcnt vmcnt(3)
	v_mfma_f32_16x16x32_bf16 v[4:7], v[12:15], v[80:83], v[4:7]
	ds_read_b128 v[12:15], v44 offset:128
	ds_read_b128 v[134:137], v44 offset:43584
	s_waitcnt lgkmcnt(1)
	v_mfma_f32_16x16x32_bf16 v[8:11], v[12:15], v[56:59], v[8:11]
	s_waitcnt vmcnt(2)
	v_mfma_f32_16x16x32_bf16 v[4:7], v[12:15], v[68:71], v[4:7]
	ds_read_b128 v[12:15], v44 offset:192
	s_waitcnt lgkmcnt(0)
	v_mfma_f32_16x16x32_bf16 v[48:51], v[12:15], v[0:3], v[8:11]
	s_nop 2
	ds_read_b128 v[8:11], v44 offset:4352
	s_waitcnt vmcnt(1)
	v_mfma_f32_16x16x32_bf16 v[4:7], v[12:15], v[60:63], v[4:7]
	s_waitcnt lgkmcnt(0)
	v_mfma_f32_16x16x32_bf16 v[12:15], v[8:11], v[76:79], 0
	v_mfma_f32_16x16x32_bf16 v[8:11], v[8:11], v[84:87], 0
	v_mfma_f32_16x16x32_bf16 v[12:15], v[16:19], v[64:67], v[12:15]
	v_mfma_f32_16x16x32_bf16 v[8:11], v[16:19], v[80:83], v[8:11]
	ds_read_b128 v[16:19], v44 offset:4480
	s_waitcnt lgkmcnt(0)
	v_mfma_f32_16x16x32_bf16 v[12:15], v[16:19], v[56:59], v[12:15]
	v_mfma_f32_16x16x32_bf16 v[8:11], v[16:19], v[68:71], v[8:11]
	ds_read_b128 v[16:19], v44 offset:4544
	s_waitcnt lgkmcnt(0)
	v_mfma_f32_16x16x32_bf16 v[52:55], v[16:19], v[0:3], v[12:15]
	s_nop 3
	ds_read_b128 v[12:15], v44 offset:8704
	v_mfma_f32_16x16x32_bf16 v[8:11], v[16:19], v[60:63], v[8:11]
	s_waitcnt lgkmcnt(0)
	v_mfma_f32_16x16x32_bf16 v[16:19], v[12:15], v[76:79], 0
	v_mfma_f32_16x16x32_bf16 v[12:15], v[12:15], v[84:87], 0
	v_mfma_f32_16x16x32_bf16 v[16:19], v[20:23], v[64:67], v[16:19]
	v_mfma_f32_16x16x32_bf16 v[12:15], v[20:23], v[80:83], v[12:15]
	ds_read_b128 v[20:23], v44 offset:8832
	s_waitcnt lgkmcnt(0)
	v_mfma_f32_16x16x32_bf16 v[16:19], v[20:23], v[56:59], v[16:19]
	v_mfma_f32_16x16x32_bf16 v[12:15], v[20:23], v[68:71], v[12:15]
	ds_read_b128 v[20:23], v44 offset:8896
	s_waitcnt lgkmcnt(0)
	v_mfma_f32_16x16x32_bf16 v[72:75], v[20:23], v[0:3], v[16:19]
	s_nop 3
	ds_read_b128 v[16:19], v28
	v_mfma_f32_16x16x32_bf16 v[12:15], v[20:23], v[60:63], v[12:15]
	s_waitcnt lgkmcnt(0)
	v_mfma_f32_16x16x32_bf16 v[20:23], v[16:19], v[76:79], 0
	v_mfma_f32_16x16x32_bf16 v[16:19], v[16:19], v[84:87], 0
	v_mfma_f32_16x16x32_bf16 v[20:23], v[24:27], v[64:67], v[20:23]
	v_mfma_f32_16x16x32_bf16 v[16:19], v[24:27], v[80:83], v[16:19]
	ds_read_b128 v[24:27], v28 offset:128
	s_waitcnt lgkmcnt(0)
	v_mfma_f32_16x16x32_bf16 v[20:23], v[24:27], v[56:59], v[20:23]
	v_mfma_f32_16x16x32_bf16 v[16:19], v[24:27], v[68:71], v[16:19]
	ds_read_b128 v[24:27], v28 offset:192
	ds_read_b128 v[28:31], v44 offset:17472
	s_waitcnt lgkmcnt(1)
	v_mfma_f32_16x16x32_bf16 v[88:91], v[24:27], v[0:3], v[20:23]
	s_nop 2
	ds_read_b128 v[20:23], v44 offset:17408
	v_mfma_f32_16x16x32_bf16 v[16:19], v[24:27], v[60:63], v[16:19]
	s_waitcnt lgkmcnt(0)
	v_mfma_f32_16x16x32_bf16 v[24:27], v[20:23], v[76:79], 0
	v_mfma_f32_16x16x32_bf16 v[20:23], v[20:23], v[84:87], 0
	v_mfma_f32_16x16x32_bf16 v[24:27], v[28:31], v[64:67], v[24:27]
	v_mfma_f32_16x16x32_bf16 v[20:23], v[28:31], v[80:83], v[20:23]
	ds_read_b128 v[28:31], v44 offset:17536
	s_waitcnt lgkmcnt(0)
	v_mfma_f32_16x16x32_bf16 v[24:27], v[28:31], v[56:59], v[24:27]
	v_mfma_f32_16x16x32_bf16 v[20:23], v[28:31], v[68:71], v[20:23]
	ds_read_b128 v[28:31], v44 offset:17600
	s_waitcnt lgkmcnt(0)
; #define LAS __attribute__((address_space(3)))
; __device__ __forceinline__ void attn_item(const bf16_t* Z, const float* ck, const float* cv, const float* btab, const float* sinks, bf16_t* MIX, int item, LAS unsigned char* lds, int tid, int wave, int lane) {
;     ...
;         for (int kk = 0; kk < 4; ++kk) { const bf16x8 Kf = *(const LAS bf16x8*)(Ks + (16 * mb + c16) * KS_STRIDE + 32 * kk + 8 * g);
;             sacc[mb][0] = __builtin_amdgcn_mfma_f32_16x16x32_bf16(Kf, Qf[0][kk], sacc[mb][0], 0, 0, 0);
;             sacc[mb][1] = __builtin_amdgcn_mfma_f32_16x16x32_bf16(Kf, Qf[1][kk], sacc[mb][1], 0, 0, 0); } }
;     float inv[2];
;     const float scale = 0.08838834764831845f;
; #pragma unroll
;     for (int nb = 0; nb < 2; ++nb) {
;         const int qidx = qhalf * 32 + nb * 16 + c16; float mx = -3.0e38f;
; #pragma unroll
;         for (int mb = 0; mb < 12; ++mb)
; #pragma unroll
;             for (int i = 0; i < 4; ++i) { const int kidx = 16 * mb + 4 * g + i; float s = sacc[mb][nb][i] * scale + bts[gh * 256 + kidx - qidx + 63]; s = kidx < kmin ? -1e30f : s; sacc[mb][nb][i] = s; mx = fmaxf(mx, s); }
;         mx = fmaxf(mx, __shfl_xor(mx, 16)); mx = fmaxf(mx, __shfl_xor(mx, 32)); mx = fmaxf(mx, sink);
	v_mfma_f32_16x16x32_bf16 v[92:95], v[28:31], v[0:3], v[24:27]
	s_nop 3
	ds_read_b128 v[24:27], v44 offset:21760
	v_mfma_f32_16x16x32_bf16 v[20:23], v[28:31], v[60:63], v[20:23]
	s_waitcnt lgkmcnt(0)
	v_mfma_f32_16x16x32_bf16 v[28:31], v[24:27], v[76:79], 0
	v_mfma_f32_16x16x32_bf16 v[24:27], v[24:27], v[84:87], 0
	v_mfma_f32_16x16x32_bf16 v[28:31], v[32:35], v[64:67], v[28:31]
	v_mfma_f32_16x16x32_bf16 v[24:27], v[32:35], v[80:83], v[24:27]
	ds_read_b128 v[32:35], v44 offset:21888
	s_waitcnt lgkmcnt(0)
	v_mfma_f32_16x16x32_bf16 v[28:31], v[32:35], v[56:59], v[28:31]
	v_mfma_f32_16x16x32_bf16 v[24:27], v[32:35], v[68:71], v[24:27]
	ds_read_b128 v[32:35], v44 offset:21952
	s_waitcnt lgkmcnt(0)
	v_mfma_f32_16x16x32_bf16 v[96:99], v[32:35], v[0:3], v[28:31]
	s_nop 3
	ds_read_b128 v[28:31], v44 offset:26112
	v_mfma_f32_16x16x32_bf16 v[24:27], v[32:35], v[60:63], v[24:27]
	s_waitcnt lgkmcnt(0)
	v_mfma_f32_16x16x32_bf16 v[32:35], v[28:31], v[76:79], 0
	v_mfma_f32_16x16x32_bf16 v[28:31], v[28:31], v[84:87], 0
	v_mfma_f32_16x16x32_bf16 v[32:35], v[36:39], v[64:67], v[32:35]
	v_mfma_f32_16x16x32_bf16 v[28:31], v[36:39], v[80:83], v[28:31]
	ds_read_b128 v[36:39], v44 offset:26240
	s_waitcnt lgkmcnt(0)
	v_mfma_f32_16x16x32_bf16 v[32:35], v[36:39], v[56:59], v[32:35]
	v_mfma_f32_16x16x32_bf16 v[28:31], v[36:39], v[68:71], v[28:31]
	ds_read_b128 v[36:39], v44 offset:26304
	s_waitcnt lgkmcnt(0)
	v_mfma_f32_16x16x32_bf16 v[100:103], v[36:39], v[0:3], v[32:35]
	s_nop 3
	ds_read_b128 v[32:35], v46
	v_mfma_f32_16x16x32_bf16 v[28:31], v[36:39], v[60:63], v[28:31]
	s_waitcnt lgkmcnt(0)
	v_mfma_f32_16x16x32_bf16 v[36:39], v[32:35], v[76:79], 0
	v_mfma_f32_16x16x32_bf16 v[32:35], v[32:35], v[84:87], 0
	v_mfma_f32_16x16x32_bf16 v[36:39], v[40:43], v[64:67], v[36:39]
	v_mfma_f32_16x16x32_bf16 v[32:35], v[40:43], v[80:83], v[32:35]
	ds_read_b128 v[40:43], v46 offset:128
	s_waitcnt lgkmcnt(0)
	v_mfma_f32_16x16x32_bf16 v[36:39], v[40:43], v[56:59], v[36:39]
	v_mfma_f32_16x16x32_bf16 v[32:35], v[40:43], v[68:71], v[32:35]
	ds_read_b128 v[40:43], v46 offset:192
	s_waitcnt lgkmcnt(0)
	v_mfma_f32_16x16x32_bf16 v[104:107], v[40:43], v[0:3], v[36:39]
	s_nop 3
	ds_read_b128 v[36:39], v44 offset:34816
	v_mfma_f32_16x16x32_bf16 v[32:35], v[40:43], v[60:63], v[32:35]
	s_waitcnt lgkmcnt(0)
	v_mfma_f32_16x16x32_bf16 v[40:43], v[36:39], v[76:79], 0
	v_mfma_f32_16x16x32_bf16 v[36:39], v[36:39], v[84:87], 0
	v_mfma_f32_16x16x32_bf16 v[40:43], v[108:111], v[64:67], v[40:43]
	v_mfma_f32_16x16x32_bf16 v[36:39], v[108:111], v[80:83], v[36:39]
	ds_read_b128 v[108:111], v44 offset:34944
	s_waitcnt lgkmcnt(0)
	v_mfma_f32_16x16x32_bf16 v[40:43], v[108:111], v[56:59], v[40:43]
	v_mfma_f32_16x16x32_bf16 v[36:39], v[108:111], v[68:71], v[36:39]
	v_mfma_f32_16x16x32_bf16 v[108:111], v[112:115], v[0:3], v[40:43]
	s_nop 5
	ds_read_b128 v[40:43], v44 offset:39168
	v_mfma_f32_16x16x32_bf16 v[36:39], v[112:115], v[60:63], v[36:39]
	s_waitcnt lgkmcnt(0)
	v_mfma_f32_16x16x32_bf16 v[112:115], v[40:43], v[76:79], 0
	v_mfma_f32_16x16x32_bf16 v[40:43], v[40:43], v[84:87], 0
	v_mfma_f32_16x16x32_bf16 v[112:115], v[116:119], v[64:67], v[112:115]
	v_mfma_f32_16x16x32_bf16 v[40:43], v[116:119], v[80:83], v[40:43]
	ds_read_b128 v[116:119], v44 offset:39296
	s_waitcnt lgkmcnt(0)
	v_mfma_f32_16x16x32_bf16 v[112:115], v[116:119], v[56:59], v[112:115]
	v_mfma_f32_16x16x32_bf16 v[40:43], v[116:119], v[68:71], v[40:43]
	ds_read_b128 v[116:119], v44 offset:39360
	s_waitcnt lgkmcnt(0)
	v_mfma_f32_16x16x32_bf16 v[112:115], v[116:119], v[0:3], v[112:115]
	v_mfma_f32_16x16x32_bf16 v[40:43], v[116:119], v[60:63], v[40:43]
	ds_read_b128 v[116:119], v44 offset:43520
	s_waitcnt lgkmcnt(0)
	v_mfma_f32_16x16x32_bf16 v[130:133], v[116:119], v[76:79], 0
	v_mfma_f32_16x16x32_bf16 v[116:119], v[116:119], v[84:87], 0
	v_mfma_f32_16x16x32_bf16 v[130:133], v[134:137], v[64:67], v[130:133]
	v_mfma_f32_16x16x32_bf16 v[116:119], v[134:137], v[80:83], v[116:119]
	ds_read_b128 v[134:137], v44 offset:43648
	ds_read_b128 v[44:47], v44 offset:43712
	s_waitcnt lgkmcnt(1)
	v_mfma_f32_16x16x32_bf16 v[130:133], v[134:137], v[56:59], v[130:133]
	v_mfma_f32_16x16x32_bf16 v[134:137], v[134:137], v[68:71], v[116:119]
	s_waitcnt lgkmcnt(0)
	v_mfma_f32_16x16x32_bf16 v[116:119], v[44:47], v[0:3], v[130:133]
	s_nop 4
	ds_read_b128 v[130:133], v124
	s_waitcnt lgkmcnt(0)
	v_mfma_f32_16x16x32_bf16 v[76:79], v[130:133], v[76:79], 0
	v_mfma_f32_16x16x32_bf16 v[84:87], v[130:133], v[84:87], 0
	ds_read_b128 v[130:133], v124 offset:64
	s_waitcnt lgkmcnt(0)
	v_mfma_f32_16x16x32_bf16 v[64:67], v[130:133], v[64:67], v[76:79]
	v_mfma_f32_16x16x32_bf16 v[76:79], v[130:133], v[80:83], v[84:87]
	ds_read_b128 v[80:83], v124 offset:128
	s_waitcnt lgkmcnt(0)
	v_mfma_f32_16x16x32_bf16 v[56:59], v[80:83], v[56:59], v[64:67]
	v_mfma_f32_16x16x32_bf16 v[64:67], v[80:83], v[68:71], v[76:79]
	ds_read_b128 v[68:71], v124 offset:192
	v_mfma_f32_16x16x32_bf16 v[44:47], v[44:47], v[60:63], v[134:137]
	s_waitcnt lgkmcnt(0)
	v_mfma_f32_16x16x32_bf16 v[56:59], v[68:71], v[0:3], v[56:59]
	v_mfma_f32_16x16x32_bf16 v[0:3], v[68:71], v[60:63], v[64:67]
	v_and_b32_e32 v61, 64, v144
	v_xor_b32_e32 v60, 16, v144
	v_add_u32_e32 v61, 64, v61
	v_cmp_lt_i32_e32 vcc, v60, v61
	v_lshlrev_b32_e32 v62, 2, v127
	v_cmp_gt_u32_e64 s[68:69], s66, v62
	v_cndmask_b32_e32 v60, v144, v60, vcc
	v_lshlrev_b32_e32 v151, 2, v60
	v_xor_b32_e32 v60, 32, v144
	v_cmp_lt_i32_e32 vcc, v60, v61
	s_nop 1
	v_cndmask_b32_e32 v60, v144, v60, vcc
	v_lshlrev_b32_e32 v152, 2, v60
	v_sub_u32_e32 v60, s6, v126
	v_lshlrev_b32_e32 v60, 2, v60
	v_add3_u32 v156, s78, v60, v122
	ds_read2_b32 v[60:61], v156 offset0:63 offset1:79
	v_readlane_b32 s6, v236, 39
	ds_read2_b32 v[154:155], v156 offset0:191 offset1:207
	s_waitcnt lgkmcnt(1)
; __device__ __forceinline__ void attn_item(const bf16_t* Z, const float* ck, const float* cv, const float* btab, const float* sinks, bf16_t* MIX, int item, LAS unsigned char* lds, int tid, int wave, int lane) {
;     ...
;     for (int nb = 0; nb < 2; ++nb) {
;         const int qidx = qhalf * 32 + nb * 16 + c16; float mx = -3.0e38f;
; #pragma unroll
;         for (int mb = 0; mb < 12; ++mb)
; #pragma unroll
;             for (int i = 0; i < 4; ++i) { const int kidx = 16 * mb + 4 * g + i; float s = sacc[mb][nb][i] * scale + bts[gh * 256 + kidx - qidx + 63]; s = kidx < kmin ? -1e30f : s; sacc[mb][nb][i] = s; mx = fmaxf(mx, s); }
;         mx = fmaxf(mx, __shfl_xor(mx, 16)); mx = fmaxf(mx, __shfl_xor(mx, 32)); mx = fmaxf(mx, sink);
	v_fmamk_f32 v48, v48, 0x3db504f3, v60
	v_sub_u32_e32 v60, s6, v126
	v_lshlrev_b32_e32 v60, 2, v60
	v_add3_u32 v153, s78, v60, v122
	ds_read2_b32 v[78:79], v153 offset0:79 offset1:80
	ds_read2_b32 v[80:81], v153 offset0:80 offset1:81
	ds_read2_b32 v[82:83], v153 offset0:81 offset1:82
	ds_read2_b32 v[84:85], v153 offset0:95 offset1:96
	v_cndmask_b32_e64 v158, v48, v145, s[68:69]
	v_or_b32_e32 v48, 1, v62
	s_waitcnt lgkmcnt(3)
	v_fmamk_f32 v49, v49, 0x3db504f3, v79
	v_cmp_gt_u32_e64 s[70:71], s66, v48
	ds_read2_b32 v[86:87], v153 offset0:96 offset1:97
	ds_read2_b32 v[122:123], v153 offset0:97 offset1:98
	ds_read2_b32 v[124:125], v153 offset0:111 offset1:112
	ds_read2_b32 v[126:127], v153 offset0:112 offset1:113
	v_cndmask_b32_e64 v79, v49, v145, s[70:71]
	v_or_b32_e32 v49, 2, v62
	v_cmp_gt_u32_e64 s[6:7], s66, v49
	v_or_b32_e32 v49, 3, v62
	s_waitcnt lgkmcnt(6)
	v_fmamk_f32 v50, v50, 0x3db504f3, v81
	v_cmp_gt_u32_e64 s[8:9], s66, v49
	v_or_b32_e32 v49, 16, v62
	v_cndmask_b32_e64 v81, v50, v145, s[6:7]
	s_waitcnt lgkmcnt(5)
	v_fmamk_f32 v50, v51, 0x3db504f3, v83
	v_cmp_gt_u32_e64 s[10:11], s66, v49
	v_or_b32_e32 v49, 17, v62
	v_cndmask_b32_e64 v83, v50, v145, s[8:9]
	s_waitcnt lgkmcnt(4)
	v_fmamk_f32 v50, v53, 0x3db504f3, v85
	v_cmp_gt_u32_e64 s[12:13], s66, v49
	v_or_b32_e32 v49, 18, v62
	v_max3_f32 v48, v158, s75, v79
	v_fmac_f32_e32 v61, 0x3db504f3, v52
	v_cndmask_b32_e64 v85, v50, v145, s[12:13]
	s_waitcnt lgkmcnt(3)
	v_fmamk_f32 v50, v54, 0x3db504f3, v87
	v_cmp_gt_u32_e64 s[14:15], s66, v49
	v_or_b32_e32 v49, 19, v62
	v_max3_f32 v48, v48, v81, v83
	v_cndmask_b32_e64 v159, v61, v145, s[10:11]
	v_cndmask_b32_e64 v87, v50, v145, s[14:15]
	s_waitcnt lgkmcnt(2)
	v_fmamk_f32 v50, v55, 0x3db504f3, v123
	v_cmp_gt_u32_e64 s[16:17], s66, v49
	v_max3_f32 v48, v48, v159, v85
	v_or_b32_e32 v51, 32, v62
	v_cndmask_b32_e64 v123, v50, v145, s[16:17]
	v_max3_f32 v50, v48, v87, v123
	ds_read2_b32 v[48:49], v156 offset0:95 offset1:111
	v_cmp_gt_u32_e64 s[18:19], s66, v51
	s_waitcnt lgkmcnt(2)
	v_fmamk_f32 v51, v73, 0x3db504f3, v125
	ds_read2_b32 v[130:131], v153 offset0:113 offset1:114
	ds_read2_b32 v[132:133], v153 offset0:127 offset1:128
	ds_read2_b32 v[134:135], v153 offset0:129 offset1:130
	ds_read2_b32 v[138:139], v153 offset0:161 offset1:162
	s_waitcnt lgkmcnt(4)
	v_fmamk_f32 v48, v72, 0x3db504f3, v48
	v_cndmask_b32_e64 v160, v48, v145, s[18:19]
	v_or_b32_e32 v48, 33, v62
	v_cmp_gt_u32_e64 s[20:21], s66, v48
	v_fmac_f32_e32 v49, 0x3db504f3, v88
	ds_read2_b32 v[136:137], v153 offset0:145 offset1:146
	ds_read2_b32 v[54:55], v153 offset0:239 offset1:240
	v_cndmask_b32_e64 v125, v51, v145, s[20:21]
	v_max3_f32 v48, v50, v160, v125
	v_or_b32_e32 v50, 34, v62
	v_cmp_gt_u32_e64 s[22:23], s66, v50
	v_or_b32_e32 v50, 35, v62
	v_cmp_gt_u32_e64 s[24:25], s66, v50
	v_or_b32_e32 v50, 48, v62
	v_cmp_gt_u32_e64 s[26:27], s66, v50
	s_waitcnt lgkmcnt(4)
	v_fmamk_f32 v50, v89, 0x3db504f3, v133
	ds_read2_b32 v[88:89], v153 offset0:128 offset1:129
	v_fmamk_f32 v51, v74, 0x3db504f3, v127
	v_cndmask_b32_e64 v161, v49, v145, s[26:27]
	v_or_b32_e32 v49, 49, v62
	v_cndmask_b32_e64 v127, v51, v145, s[22:23]
	v_fmamk_f32 v51, v75, 0x3db504f3, v131
	v_cmp_gt_u32_e64 s[28:29], s66, v49
	v_or_b32_e32 v49, 50, v62
	v_cndmask_b32_e64 v131, v51, v145, s[24:25]
	v_cndmask_b32_e64 v133, v50, v145, s[28:29]
	v_cmp_gt_u32_e64 s[30:31], s66, v49
	v_or_b32_e32 v49, 51, v62
	ds_read2_b32 v[74:75], v153 offset0:192 offset1:193
	s_waitcnt lgkmcnt(1)
	v_fmamk_f32 v50, v90, 0x3db504f3, v89
	v_max3_f32 v48, v48, v127, v131
	v_cndmask_b32_e64 v89, v50, v145, s[30:31]
	v_fmamk_f32 v50, v91, 0x3db504f3, v135
	v_cmp_gt_u32_e64 s[34:35], s66, v49
	v_max3_f32 v48, v48, v161, v133
	ds_read2_b32 v[90:91], v153 offset0:143 offset1:144
	ds_read2_b32 v[140:141], v153 offset0:177 offset1:178
	ds_read2_b32 v[64:65], v153 offset0:223 offset1:224
	v_cndmask_b32_e64 v135, v50, v145, s[34:35]
	v_max3_f32 v50, v48, v89, v135
	ds_read2_b32 v[48:49], v156 offset0:127 offset1:143
	v_or_b32_e32 v51, 64, v62
	v_cmp_gt_u32_e64 s[36:37], s66, v51
	s_waitcnt lgkmcnt(3)
	v_fmamk_f32 v51, v93, 0x3db504f3, v91
	ds_read2_b32 v[76:77], v153 offset0:191 offset1:192
	ds_read2_b32 v[60:61], v153 offset0:225 offset1:226
	s_waitcnt lgkmcnt(2)
	v_fmamk_f32 v48, v92, 0x3db504f3, v48
	ds_read2_b32 v[92:93], v153 offset0:144 offset1:145
	v_cndmask_b32_e64 v162, v48, v145, s[36:37]
	v_or_b32_e32 v48, 0x41, v62
	v_cmp_gt_u32_e64 s[38:39], s66, v48
	v_fmac_f32_e32 v49, 0x3db504f3, v96
	ds_read2_b32 v[72:73], v153 offset0:193 offset1:194
	v_cndmask_b32_e64 v91, v51, v145, s[38:39]
	v_max3_f32 v48, v50, v162, v91
	v_or_b32_e32 v50, 0x42, v62
	s_waitcnt lgkmcnt(1)
	v_fmamk_f32 v51, v94, 0x3db504f3, v93
	v_cmp_gt_u32_e64 s[40:41], s66, v50
	v_or_b32_e32 v50, 0x43, v62
	v_cmp_gt_u32_e64 s[42:43], s66, v50
	v_cndmask_b32_e64 v93, v51, v145, s[40:41]
	v_fmamk_f32 v51, v95, 0x3db504f3, v137
	ds_read2_b32 v[94:95], v153 offset0:159 offset1:160
	v_or_b32_e32 v50, 0x50, v62
	v_cmp_gt_u32_e64 s[44:45], s66, v50
	v_cndmask_b32_e64 v137, v51, v145, s[42:43]
	ds_read2_b32 v[70:71], v153 offset0:207 offset1:208
	s_waitcnt lgkmcnt(1)
	v_fmamk_f32 v50, v97, 0x3db504f3, v95
	ds_read2_b32 v[96:97], v153 offset0:160 offset1:161
	v_cndmask_b32_e64 v163, v49, v145, s[44:45]
	v_or_b32_e32 v49, 0x51, v62
	v_cmp_gt_u32_e64 s[46:47], s66, v49
	v_or_b32_e32 v49, 0x52, v62
	v_cmp_gt_u32_e64 s[48:49], s66, v49
	v_cndmask_b32_e64 v95, v50, v145, s[46:47]
	s_waitcnt lgkmcnt(0)
; __device__ __forceinline__ void attn_item(const bf16_t* Z, const float* ck, const float* cv, const float* btab, const float* sinks, bf16_t* MIX, int item, LAS unsigned char* lds, int tid, int wave, int lane) {
;     ...
;             for (int i = 0; i < 4; ++i) { const int kidx = 16 * mb + 4 * g + i; float s = sacc[mb][nb][i] * scale + bts[gh * 256 + kidx - qidx + 63]; s = kidx < kmin ? -1e30f : s; sacc[mb][nb][i] = s; mx = fmaxf(mx, s); }
;         mx = fmaxf(mx, __shfl_xor(mx, 16)); mx = fmaxf(mx, __shfl_xor(mx, 32)); mx = fmaxf(mx, sink);
;         float sum = 0.f;
; #pragma unroll
;         for (int mb = 0; mb < 12; ++mb)
; #pragma unroll
;             for (int i = 0; i < 4; ++i) { const float e = __expf(sacc[mb][nb][i] - mx); sum += e; sacc[mb][nb][i] = e; }
;         sum += __shfl_xor(sum, 16); sum += __shfl_xor(sum, 32); sum += __expf(sink - mx);
	v_fmamk_f32 v50, v98, 0x3db504f3, v97
	v_or_b32_e32 v49, 0x53, v62
	v_max3_f32 v48, v48, v93, v137
	v_cndmask_b32_e64 v97, v50, v145, s[48:49]
	v_fmamk_f32 v50, v99, 0x3db504f3, v139
	v_cmp_gt_u32_e64 s[50:51], s66, v49
	v_max3_f32 v48, v48, v163, v95
	ds_read2_b32 v[98:99], v153 offset0:175 offset1:176
	ds_read2_b32 v[68:69], v153 offset0:208 offset1:209
	v_cndmask_b32_e64 v139, v50, v145, s[50:51]
	v_max3_f32 v50, v48, v97, v139
	ds_read2_b32 v[48:49], v156 offset0:159 offset1:175
	v_or_b32_e32 v51, 0x60, v62
	s_waitcnt lgkmcnt(2)
	v_fmamk_f32 v52, v101, 0x3db504f3, v99
	v_cmp_gt_u32_e64 s[52:53], s66, v51
	v_or_b32_e32 v51, 0x61, v62
	s_waitcnt lgkmcnt(0)
	v_fmamk_f32 v48, v100, 0x3db504f3, v48
	ds_read2_b32 v[100:101], v153 offset0:176 offset1:177
	ds_read2_b32 v[66:67], v153 offset0:209 offset1:210
	v_cmp_gt_u32_e64 s[54:55], s66, v51
	v_or_b32_e32 v51, 0x62, v62
	v_cmp_gt_u32_e64 s[56:57], s66, v51
	v_or_b32_e32 v51, 0x63, v62
	v_cmp_gt_u32_e64 s[58:59], s66, v51
	v_or_b32_e32 v51, 0x70, v62
	v_cndmask_b32_e64 v99, v52, v145, s[54:55]
	s_waitcnt lgkmcnt(1)
	v_fmamk_f32 v52, v102, 0x3db504f3, v101
	v_fmac_f32_e32 v49, 0x3db504f3, v104
	v_cmp_gt_u32_e64 s[60:61], s66, v51
	v_cndmask_b32_e64 v48, v48, v145, s[52:53]
	v_cndmask_b32_e64 v101, v52, v145, s[56:57]
	v_fmamk_f32 v52, v103, 0x3db504f3, v141
	v_cndmask_b32_e64 v103, v49, v145, s[60:61]
	v_or_b32_e32 v49, 0x71, v62
	v_max3_f32 v50, v50, v48, v99
	v_cndmask_b32_e64 v102, v52, v145, s[58:59]
	v_fmamk_f32 v51, v105, 0x3db504f3, v77
	v_cmp_gt_u32_e64 s[62:63], s66, v49
	v_max3_f32 v50, v50, v101, v102
	v_fmac_f32_e32 v155, 0x3db504f3, v112
	v_cndmask_b32_e64 v104, v51, v145, s[62:63]
	v_max3_f32 v49, v50, v103, v104
	v_or_b32_e32 v50, 0x72, v62
	v_cmp_gt_u32_e64 s[64:65], s66, v50
	v_or_b32_e32 v50, 0x73, v62
	ds_read2_b32 v[62:63], v153 offset0:224 offset1:225
	ds_read2_b32 v[52:53], v153 offset0:240 offset1:241
	v_fmamk_f32 v51, v106, 0x3db504f3, v75
	v_cndmask_b32_e64 v105, v51, v145, s[64:65]
	v_fmamk_f32 v51, v107, 0x3db504f3, v73
	v_cmp_gt_u32_e64 s[66:67], s66, v50
	v_fmamk_f32 v107, v108, 0x3db504f3, v154
	v_fmamk_f32 v108, v109, 0x3db504f3, v71
	v_cndmask_b32_e64 v106, v51, v145, s[66:67]
	ds_read2_b32 v[50:51], v153 offset0:241 offset1:242
	s_waitcnt lgkmcnt(2)
	v_fmamk_f32 v112, v114, 0x3db504f3, v63
	ds_read_b32 v114, v156 offset:892
	v_max3_f32 v49, v49, v105, v106
	v_max3_f32 v49, v49, v107, v108
	v_fmamk_f32 v109, v110, 0x3db504f3, v69
	v_fmamk_f32 v110, v111, 0x3db504f3, v67
	v_fmamk_f32 v111, v113, 0x3db504f3, v65
	v_fmamk_f32 v113, v115, 0x3db504f3, v61
	s_waitcnt lgkmcnt(0)
	v_fmac_f32_e32 v114, 0x3db504f3, v116
	v_fmamk_f32 v115, v117, 0x3db504f3, v55
	v_fmamk_f32 v116, v118, 0x3db504f3, v53
	v_fmamk_f32 v117, v119, 0x3db504f3, v51
	ds_read2_b32 v[118:119], v156 offset0:239 offset1:240
	v_max3_f32 v49, v49, v109, v110
	ds_read2_b32 v[156:157], v156 offset0:241 offset1:242
	v_max3_f32 v49, v49, v155, v111
	v_max3_f32 v49, v49, v112, v113
	v_max3_f32 v49, v49, v114, v115
	v_max3_f32 v49, v49, v116, v117
	s_waitcnt lgkmcnt(1)
	v_fmamk_f32 v118, v56, 0x3db504f3, v118
	v_fmac_f32_e32 v119, 0x3db504f3, v57
	v_max3_f32 v49, v49, v118, v119
	s_waitcnt lgkmcnt(0)
	v_fmamk_f32 v141, v58, 0x3db504f3, v156
	v_fmac_f32_e32 v157, 0x3db504f3, v59
	v_max3_f32 v49, v49, v141, v157
	ds_bpermute_b32 v51, v151, v49
	v_fmac_f32_e32 v52, 0x3db504f3, v1
	ds_read_b32 v1, v153 offset:968
	v_fmac_f32_e32 v78, 0x3db504f3, v8
	v_fmac_f32_e32 v80, 0x3db504f3, v9
	s_waitcnt lgkmcnt(1)
	v_max_f32_e32 v51, v51, v51
	v_max_f32_e32 v49, v49, v51
	ds_bpermute_b32 v51, v152, v49
	v_fmac_f32_e32 v82, 0x3db504f3, v10
	v_fmac_f32_e32 v84, 0x3db504f3, v12
	v_fmac_f32_e32 v86, 0x3db504f3, v13
	v_fmac_f32_e32 v122, 0x3db504f3, v14
	s_waitcnt vmcnt(0) lgkmcnt(0)
	v_max3_f32 v154, v49, v51, v150
	v_sub_f32_e32 v49, v158, v154
	v_mul_f32_e32 v49, 0x3fb8aa3b, v49
	v_sub_f32_e32 v51, v79, v154
	v_exp_f32_e32 v49, v49
	v_mul_f32_e32 v51, 0x3fb8aa3b, v51
	v_exp_f32_e32 v51, v51
	v_sub_f32_e32 v61, v123, v154
	v_add_f32_e32 v53, 0, v49
	v_mul_f32_e32 v61, 0x3fb8aa3b, v61
	v_add_f32_e32 v55, v51, v53
	v_sub_f32_e32 v53, v81, v154
	v_mul_f32_e32 v53, 0x3fb8aa3b, v53
	v_exp_f32_e32 v53, v53
	v_exp_f32_e32 v61, v61
	v_sub_f32_e32 v77, v135, v154
	v_mul_f32_e32 v77, 0x3fb8aa3b, v77
	v_add_f32_e32 v56, v53, v55
	v_sub_f32_e32 v55, v83, v154
	v_mul_f32_e32 v55, 0x3fb8aa3b, v55
	v_exp_f32_e32 v55, v55
	v_exp_f32_e32 v77, v77
	v_sub_f32_e32 v48, v48, v154
	v_mul_f32_e32 v48, 0x3fb8aa3b, v48
	v_add_f32_e32 v57, v55, v56
	v_sub_f32_e32 v56, v159, v154
	v_mul_f32_e32 v56, 0x3fb8aa3b, v56
	v_exp_f32_e32 v56, v56
	v_sub_f32_e32 v123, v157, v154
	v_mul_f32_e32 v123, 0x3fb8aa3b, v123
	v_exp_f32_e32 v123, v123
	v_add_f32_e32 v58, v56, v57
	v_sub_f32_e32 v57, v85, v154
	v_mul_f32_e32 v57, 0x3fb8aa3b, v57
	v_exp_f32_e32 v57, v57
	v_fmac_f32_e32 v124, 0x3db504f3, v16
	v_fmac_f32_e32 v126, 0x3db504f3, v17
	v_fmac_f32_e32 v130, 0x3db504f3, v18
	v_add_f32_e32 v59, v57, v58
	v_sub_f32_e32 v58, v87, v154
	v_mul_f32_e32 v58, 0x3fb8aa3b, v58
	v_exp_f32_e32 v58, v58
	v_fmac_f32_e32 v132, 0x3db504f3, v20
	v_fmac_f32_e32 v88, 0x3db504f3, v21
	v_cndmask_b32_e64 v21, v88, v145, s[38:39]
	v_add_f32_e32 v59, v58, v59
	v_add_f32_e32 v63, v61, v59
	v_sub_f32_e32 v59, v160, v154
	v_mul_f32_e32 v59, 0x3fb8aa3b, v59
	v_exp_f32_e32 v59, v59
	v_fmac_f32_e32 v134, 0x3db504f3, v22
	v_cndmask_b32_e64 v20, v134, v145, s[40:41]
	v_fmac_f32_e32 v90, 0x3db504f3, v24
	v_add_f32_e32 v65, v59, v63
	v_sub_f32_e32 v63, v125, v154
	v_mul_f32_e32 v63, 0x3fb8aa3b, v63
	v_exp_f32_e32 v63, v63
	v_fmac_f32_e32 v92, 0x3db504f3, v25
	v_cndmask_b32_e64 v18, v90, v145, s[44:45]
; __device__ __forceinline__ unsigned cvt_pk_bf16(float lo, float hi) { const f32x2_cv v = {lo, hi}; return __builtin_bit_cast(unsigned, __builtin_convertvector(v, bf16x2_cv)); }
; __device__ __forceinline__ void attn_item(const bf16_t* Z, const float* ck, const float* cv, const float* btab, const float* sinks, bf16_t* MIX, int item, LAS unsigned char* lds, int tid, int wave, int lane) {
;     ...
;     for (int nb = 0; nb < 2; ++nb) {
;         const int qidx = qhalf * 32 + nb * 16 + c16; float mx = -3.0e38f;
; #pragma unroll
;         for (int mb = 0; mb < 12; ++mb)
; #pragma unroll
;             for (int i = 0; i < 4; ++i) { const int kidx = 16 * mb + 4 * g + i; float s = sacc[mb][nb][i] * scale + bts[gh * 256 + kidx - qidx + 63]; s = kidx < kmin ? -1e30f : s; sacc[mb][nb][i] = s; mx = fmaxf(mx, s); }
;         mx = fmaxf(mx, __shfl_xor(mx, 16)); mx = fmaxf(mx, __shfl_xor(mx, 32)); mx = fmaxf(mx, sink);
;         float sum = 0.f;
; #pragma unroll
;         for (int mb = 0; mb < 12; ++mb)
; #pragma unroll
;             for (int i = 0; i < 4; ++i) { const float e = __expf(sacc[mb][nb][i] - mx); sum += e; sacc[mb][nb][i] = e; }
;         sum += __shfl_xor(sum, 16); sum += __shfl_xor(sum, 32); sum += __expf(sink - mx);
;         inv[nb] = 1.0f / sum;
;     }
;     bf16x8 Pf[2][6];
; #pragma unroll
;     for (int nb = 0; nb < 2; ++nb)
; #pragma unroll
;         for (int ks = 0; ks < 6; ++ks) { u32x4 p; p.x = cvt_pk_bf16(sacc[2 * ks][nb][0], sacc[2 * ks][nb][1]); p.y = cvt_pk_bf16(sacc[2 * ks][nb][2], sacc[2 * ks][nb][3]);
;             p.z = cvt_pk_bf16(sacc[2 * ks + 1][nb][0], sacc[2 * ks + 1][nb][1]); p.w = cvt_pk_bf16(sacc[2 * ks + 1][nb][2], sacc[2 * ks + 1][nb][3]); Pf[nb][ks] = __builtin_bit_cast(bf16x8, p); }
	v_cndmask_b32_e64 v17, v92, v145, s[46:47]
	v_add_f32_e32 v67, v63, v65
	v_sub_f32_e32 v65, v127, v154
	v_mul_f32_e32 v65, 0x3fb8aa3b, v65
	v_exp_f32_e32 v65, v65
	v_fmac_f32_e32 v136, 0x3db504f3, v26
	v_cndmask_b32_e64 v16, v136, v145, s[48:49]
	v_fmac_f32_e32 v94, 0x3db504f3, v28
	v_add_f32_e32 v69, v65, v67
	v_sub_f32_e32 v67, v131, v154
	v_mul_f32_e32 v67, 0x3fb8aa3b, v67
	v_exp_f32_e32 v67, v67
	v_fmac_f32_e32 v96, 0x3db504f3, v29
	v_cndmask_b32_e64 v14, v94, v145, s[52:53]
	v_cndmask_b32_e64 v13, v96, v145, s[54:55]
	v_add_f32_e32 v71, v67, v69
	v_sub_f32_e32 v69, v161, v154
	v_mul_f32_e32 v69, 0x3fb8aa3b, v69
	v_exp_f32_e32 v69, v69
	v_fmac_f32_e32 v138, 0x3db504f3, v30
	v_cndmask_b32_e64 v12, v138, v145, s[56:57]
	v_fmac_f32_e32 v98, 0x3db504f3, v32
	v_add_f32_e32 v73, v69, v71
	v_sub_f32_e32 v71, v133, v154
	v_mul_f32_e32 v71, 0x3fb8aa3b, v71
	v_exp_f32_e32 v71, v71
	v_fmac_f32_e32 v100, 0x3db504f3, v33
	v_cndmask_b32_e64 v10, v98, v145, s[60:61]
	v_cndmask_b32_e64 v9, v100, v145, s[62:63]
	v_add_f32_e32 v75, v71, v73
	v_sub_f32_e32 v73, v89, v154
	v_mul_f32_e32 v73, 0x3fb8aa3b, v73
	v_exp_f32_e32 v73, v73
	v_fmac_f32_e32 v140, 0x3db504f3, v34
	v_cndmask_b32_e64 v8, v140, v145, s[64:65]
	v_fmac_f32_e32 v76, 0x3db504f3, v36
	v_add_f32_e32 v75, v73, v75
	v_add_f32_e32 v79, v77, v75
	v_sub_f32_e32 v75, v162, v154
	v_mul_f32_e32 v75, 0x3fb8aa3b, v75
	v_exp_f32_e32 v75, v75
	v_fmac_f32_e32 v74, 0x3db504f3, v37
	v_fmac_f32_e32 v72, 0x3db504f3, v38
	v_fmac_f32_e32 v70, 0x3db504f3, v40
	v_add_f32_e32 v81, v75, v79
	v_sub_f32_e32 v79, v91, v154
	v_mul_f32_e32 v79, 0x3fb8aa3b, v79
	v_exp_f32_e32 v79, v79
	v_fmac_f32_e32 v68, 0x3db504f3, v41
	v_fmac_f32_e32 v66, 0x3db504f3, v42
	v_fmac_f32_e32 v64, 0x3db504f3, v44
	v_add_f32_e32 v83, v79, v81
	v_sub_f32_e32 v81, v93, v154
	v_mul_f32_e32 v81, 0x3fb8aa3b, v81
	v_exp_f32_e32 v81, v81
	v_sub_f32_e32 v93, v139, v154
	v_mul_f32_e32 v93, 0x3fb8aa3b, v93
	v_exp_f32_e32 v93, v93
	v_add_f32_e32 v85, v81, v83
	v_sub_f32_e32 v83, v137, v154
	v_mul_f32_e32 v83, 0x3fb8aa3b, v83
	v_exp_f32_e32 v83, v83
	v_cndmask_b32_e64 v139, v82, v145, s[14:15]
	v_cndmask_b32_e64 v82, v130, v145, s[30:31]
	v_fmac_f32_e32 v62, 0x3db504f3, v45
	v_add_f32_e32 v87, v83, v85
	v_sub_f32_e32 v85, v163, v154
	v_mul_f32_e32 v85, 0x3fb8aa3b, v85
	v_exp_f32_e32 v85, v85
	v_fmac_f32_e32 v60, 0x3db504f3, v46
	v_fmac_f32_e32 v54, 0x3db504f3, v0
	v_fmac_f32_e32 v50, 0x3db504f3, v2
	v_add_f32_e32 v89, v85, v87
	v_sub_f32_e32 v87, v95, v154
	v_mul_f32_e32 v87, 0x3fb8aa3b, v87
	v_exp_f32_e32 v87, v87
	v_fmac_f32_e32 v1, 0x3db504f3, v3
	v_cvt_pk_bf16_f32 v42, v56, v57
	v_add_u32_e32 v56, 0, v120
	v_add_f32_e32 v91, v87, v89
	v_sub_f32_e32 v89, v97, v154
	v_mul_f32_e32 v89, 0x3fb8aa3b, v89
	v_exp_f32_e32 v89, v89
	v_sub_f32_e32 v97, v101, v154
	v_mul_f32_e32 v97, 0x3fb8aa3b, v97
	v_exp_f32_e32 v97, v97
	v_add_f32_e32 v91, v89, v91
	v_add_f32_e32 v95, v93, v91
	v_exp_f32_e32 v91, v48
	v_sub_f32_e32 v101, v103, v154
	v_mul_f32_e32 v101, 0x3fb8aa3b, v101
	v_exp_f32_e32 v101, v101
	v_add_f32_e32 v48, v91, v95
	v_sub_f32_e32 v95, v99, v154
	v_mul_f32_e32 v95, 0x3fb8aa3b, v95
	v_exp_f32_e32 v95, v95
	v_sub_f32_e32 v99, v102, v154
	v_mul_f32_e32 v99, 0x3fb8aa3b, v99
	v_exp_f32_e32 v99, v99
	v_sub_f32_e32 v102, v104, v154
	v_mul_f32_e32 v102, 0x3fb8aa3b, v102
	v_sub_f32_e32 v103, v105, v154
	v_add_f32_e32 v48, v95, v48
	v_exp_f32_e32 v102, v102
	v_mul_f32_e32 v103, 0x3fb8aa3b, v103
	v_sub_f32_e32 v104, v106, v154
	v_add_f32_e32 v48, v97, v48
	v_exp_f32_e32 v103, v103
	v_mul_f32_e32 v104, 0x3fb8aa3b, v104
	v_sub_f32_e32 v105, v107, v154
	v_add_f32_e32 v48, v99, v48
	v_exp_f32_e32 v104, v104
	v_mul_f32_e32 v105, 0x3fb8aa3b, v105
	v_sub_f32_e32 v106, v108, v154
	v_add_f32_e32 v48, v101, v48
	v_exp_f32_e32 v105, v105
	v_mul_f32_e32 v106, 0x3fb8aa3b, v106
	v_sub_f32_e32 v107, v109, v154
	v_add_f32_e32 v48, v102, v48
	v_exp_f32_e32 v106, v106
	v_mul_f32_e32 v107, 0x3fb8aa3b, v107
	v_sub_f32_e32 v108, v110, v154
	v_add_f32_e32 v48, v103, v48
	v_exp_f32_e32 v107, v107
	v_mul_f32_e32 v108, 0x3fb8aa3b, v108
	v_sub_f32_e32 v109, v155, v154
	v_add_f32_e32 v48, v104, v48
	v_exp_f32_e32 v108, v108
	v_mul_f32_e32 v109, 0x3fb8aa3b, v109
	v_sub_f32_e32 v110, v111, v154
	v_add_f32_e32 v48, v105, v48
	v_exp_f32_e32 v109, v109
	v_mul_f32_e32 v110, 0x3fb8aa3b, v110
	v_sub_f32_e32 v111, v112, v154
	v_add_f32_e32 v48, v106, v48
	v_exp_f32_e32 v110, v110
	v_mul_f32_e32 v111, 0x3fb8aa3b, v111
	v_sub_f32_e32 v112, v113, v154
	v_add_f32_e32 v48, v107, v48
	v_exp_f32_e32 v111, v111
	v_mul_f32_e32 v112, 0x3fb8aa3b, v112
	v_sub_f32_e32 v113, v114, v154
	v_add_f32_e32 v48, v108, v48
	v_exp_f32_e32 v112, v112
	v_mul_f32_e32 v113, 0x3fb8aa3b, v113
	v_sub_f32_e32 v114, v115, v154
	v_add_f32_e32 v48, v109, v48
	v_exp_f32_e32 v113, v113
	v_mul_f32_e32 v114, 0x3fb8aa3b, v114
	v_sub_f32_e32 v115, v116, v154
	v_add_f32_e32 v48, v110, v48
	v_exp_f32_e32 v114, v114
	v_mul_f32_e32 v115, 0x3fb8aa3b, v115
	v_sub_f32_e32 v116, v117, v154
	v_add_f32_e32 v48, v111, v48
	v_exp_f32_e32 v115, v115
	v_mul_f32_e32 v116, 0x3fb8aa3b, v116
	v_sub_f32_e32 v117, v118, v154
	v_add_f32_e32 v48, v112, v48
	v_exp_f32_e32 v116, v116
	v_mul_f32_e32 v117, 0x3fb8aa3b, v117
	v_sub_f32_e32 v118, v119, v154
	v_add_f32_e32 v48, v113, v48
	v_exp_f32_e32 v117, v117
	v_mul_f32_e32 v118, 0x3fb8aa3b, v118
	v_sub_f32_e32 v119, v141, v154
	v_add_f32_e32 v48, v114, v48
	v_exp_f32_e32 v118, v118
	v_mul_f32_e32 v119, 0x3fb8aa3b, v119
	v_add_f32_e32 v48, v115, v48
	v_exp_f32_e32 v119, v119
	v_add_f32_e32 v48, v116, v48
	v_add_f32_e32 v48, v117, v48
	v_add_f32_e32 v48, v118, v48
	v_add_f32_e32 v48, v119, v48
	v_add_f32_e32 v48, v123, v48
	ds_bpermute_b32 v125, v151, v48
	v_cndmask_b32_e64 v141, v80, v145, s[12:13]
	v_cvt_pk_bf16_f32 v40, v49, v51
	v_cvt_pk_bf16_f32 v32, v59, v63
	v_cvt_pk_bf16_f32 v33, v65, v67
	s_waitcnt lgkmcnt(0)
; __device__ __forceinline__ void attn_item(const bf16_t* Z, const float* ck, const float* cv, const float* btab, const float* sinks, bf16_t* MIX, int item, LAS unsigned char* lds, int tid, int wave, int lane) {
;     ...
;     for (int nb = 0; nb < 2; ++nb) {
;         const int qidx = qhalf * 32 + nb * 16 + c16; float mx = -3.0e38f;
; #pragma unroll
;         for (int mb = 0; mb < 12; ++mb)
; #pragma unroll
;             for (int i = 0; i < 4; ++i) { const int kidx = 16 * mb + 4 * g + i; float s = sacc[mb][nb][i] * scale + bts[gh * 256 + kidx - qidx + 63]; s = kidx < kmin ? -1e30f : s; sacc[mb][nb][i] = s; mx = fmaxf(mx, s); }
;         mx = fmaxf(mx, __shfl_xor(mx, 16)); mx = fmaxf(mx, __shfl_xor(mx, 32)); mx = fmaxf(mx, sink);
;         float sum = 0.f;
; #pragma unroll
;         for (int mb = 0; mb < 12; ++mb)
; #pragma unroll
;             for (int i = 0; i < 4; ++i) { const float e = __expf(sacc[mb][nb][i] - mx); sum += e; sacc[mb][nb][i] = e; }
;         sum += __shfl_xor(sum, 16); sum += __shfl_xor(sum, 32); sum += __expf(sink - mx);
;         inv[nb] = 1.0f / sum;
;     }
	v_add_f32_e32 v48, v48, v125
	ds_bpermute_b32 v125, v152, v48
	v_cvt_pk_bf16_f32 v34, v69, v71
	v_cvt_pk_bf16_f32 v41, v53, v55
	v_cvt_pk_bf16_f32 v24, v75, v79
	v_cvt_pk_bf16_f32 v25, v81, v83
	s_waitcnt lgkmcnt(0)
	v_add_f32_e32 v48, v48, v125
	v_sub_f32_e32 v125, v150, v154
	v_mul_f32_e32 v125, 0x3fb8aa3b, v125
	v_exp_f32_e32 v125, v125
	ds_read2_b32 v[154:155], v153 offset0:63 offset1:64
	v_cvt_pk_bf16_f32 v26, v85, v87
	v_mov_b32_e32 v55, v121
	v_add_f32_e32 v48, v125, v48
	v_div_scale_f32 v125, vcc, v48, v48, 1.0
	v_rcp_f32_e32 v127, v125
	s_waitcnt lgkmcnt(0)
	v_fmac_f32_e32 v155, 0x3db504f3, v5
	v_fmamk_f32 v4, v4, 0x3db504f3, v154
	v_fma_f32 v131, -v125, v127, 1.0
	v_fmac_f32_e32 v127, v131, v127
	v_div_scale_f32 v131, vcc, 1.0, v48, 1.0
	v_mul_f32_e32 v133, v131, v127
	v_fma_f32 v135, -v125, v133, v131
	v_fmac_f32_e32 v133, v135, v127
	v_fma_f32 v125, -v125, v133, v131
	v_div_fmas_f32 v125, v125, v127, v133
	v_div_fixup_f32 v48, v125, v48, 1.0
	v_cndmask_b32_e64 v125, v155, v145, s[70:71]
	ds_read2_b32 v[154:155], v153 offset0:65 offset1:66
	v_cndmask_b32_e64 v127, v4, v145, s[68:69]
	v_max3_f32 v4, v127, s75, v125
	v_cndmask_b32_e64 v135, v84, v145, s[18:19]
	v_cndmask_b32_e64 v133, v86, v145, s[20:21]
	s_waitcnt lgkmcnt(0)
	v_fmamk_f32 v5, v6, 0x3db504f3, v154
	v_fmac_f32_e32 v155, 0x3db504f3, v7
	v_cndmask_b32_e64 v156, v5, v145, s[6:7]
	v_cndmask_b32_e64 v155, v155, v145, s[8:9]
	v_max3_f32 v4, v4, v156, v155
	v_cndmask_b32_e64 v154, v78, v145, s[10:11]
	v_max3_f32 v6, v4, v154, v141
	ds_read2_b32 v[4:5], v153 offset0:82 offset1:98
	v_cndmask_b32_e64 v131, v122, v145, s[22:23]
	v_cndmask_b32_e64 v86, v124, v145, s[26:27]
	v_cndmask_b32_e64 v84, v126, v145, s[28:29]
	v_cndmask_b32_e64 v78, v132, v145, s[36:37]
	s_waitcnt lgkmcnt(0)
	v_fmamk_f32 v4, v11, 0x3db504f3, v4
	v_cndmask_b32_e64 v137, v4, v145, s[16:17]
	v_max3_f32 v4, v6, v139, v137
	v_fmac_f32_e32 v5, 0x3db504f3, v15
	v_max3_f32 v4, v4, v135, v133
	v_cndmask_b32_e64 v122, v5, v145, s[24:25]
	v_max3_f32 v4, v4, v131, v122
	v_max3_f32 v6, v4, v86, v84
	ds_read2_b32 v[4:5], v153 offset0:114 offset1:130
	s_movk_i32 s8, 0x188
	v_mad_u32_u24 v49, v149, s8, v56
	v_add_u32_e32 v51, 0xc800, v49
	v_readlane_b32 s70, v236, 20
	s_waitcnt lgkmcnt(0)
	v_fmamk_f32 v4, v19, 0x3db504f3, v4
	v_cndmask_b32_e64 v80, v4, v145, s[34:35]
	v_max3_f32 v4, v6, v82, v80
	v_fmac_f32_e32 v5, 0x3db504f3, v23
	v_max3_f32 v4, v4, v78, v21
	v_cndmask_b32_e64 v19, v5, v145, s[42:43]
	v_max3_f32 v4, v4, v20, v19
	v_max3_f32 v6, v4, v18, v17
	ds_read2_b32 v[4:5], v153 offset0:146 offset1:162
	v_readlane_b32 s71, v236, 21
	v_readlane_b32 s68, v236, 18
	v_readlane_b32 s42, v236, 4
	v_readlane_b32 s69, v236, 19
	s_waitcnt lgkmcnt(0)
	v_fmamk_f32 v4, v27, 0x3db504f3, v4
	v_cndmask_b32_e64 v15, v4, v145, s[50:51]
	v_max3_f32 v4, v6, v16, v15
	ds_read2_b32 v[6:7], v153 offset0:178 offset1:194
	v_fmac_f32_e32 v5, 0x3db504f3, v31
	v_max3_f32 v4, v4, v14, v13
	v_cndmask_b32_e64 v11, v5, v145, s[58:59]
	v_max3_f32 v4, v4, v12, v11
	s_waitcnt lgkmcnt(0)
	v_fmamk_f32 v5, v35, 0x3db504f3, v6
	v_max3_f32 v4, v4, v10, v9
	v_cndmask_b32_e64 v6, v5, v145, s[66:67]
	v_max3_f32 v4, v4, v8, v6
	v_max3_f32 v4, v4, v76, v74
	v_fmac_f32_e32 v7, 0x3db504f3, v39
	v_max3_f32 v4, v4, v72, v7
	v_max3_f32 v22, v4, v70, v68
	ds_read2_b32 v[4:5], v153 offset0:210 offset1:226
	v_cvt_pk_bf16_f32 v35, v73, v77
	v_cvt_pk_bf16_f32 v27, v89, v93
	v_readlane_b32 s43, v236, 5
	s_waitcnt lgkmcnt(0)
	v_fmamk_f32 v4, v43, 0x3db504f3, v4
	v_max3_f32 v22, v22, v66, v4
	v_max3_f32 v22, v22, v64, v62
	v_fmac_f32_e32 v5, 0x3db504f3, v47
	v_max3_f32 v22, v22, v60, v5
	v_max3_f32 v0, v22, v54, v52
	v_max3_f32 v0, v0, v50, v1
	ds_bpermute_b32 v2, v151, v0
	v_cvt_pk_bf16_f32 v43, v58, v61
	s_waitcnt lgkmcnt(0)
	v_max_f32_e32 v2, v2, v2
	v_max_f32_e32 v0, v0, v2
	ds_bpermute_b32 v2, v152, v0
	s_waitcnt lgkmcnt(0)
	v_max3_f32 v0, v0, v2, v150
	v_sub_f32_e32 v3, v125, v0
	v_mul_f32_e32 v3, 0x3fb8aa3b, v3
	v_exp_f32_e32 v23, v3
	v_sub_f32_e32 v3, v156, v0
	v_mul_f32_e32 v3, 0x3fb8aa3b, v3
	v_exp_f32_e32 v28, v3
	v_sub_f32_e32 v3, v155, v0
	v_mul_f32_e32 v3, 0x3fb8aa3b, v3
	v_exp_f32_e32 v29, v3
	v_sub_f32_e32 v3, v154, v0
	v_mul_f32_e32 v3, 0x3fb8aa3b, v3
	v_exp_f32_e32 v30, v3
	v_sub_f32_e32 v3, v141, v0
	v_mul_f32_e32 v3, 0x3fb8aa3b, v3
	v_exp_f32_e32 v31, v3
	v_sub_f32_e32 v3, v139, v0
	v_mul_f32_e32 v3, 0x3fb8aa3b, v3
	v_exp_f32_e32 v36, v3
	v_sub_f32_e32 v3, v137, v0
	v_mul_f32_e32 v3, 0x3fb8aa3b, v3
	v_exp_f32_e32 v37, v3
	v_sub_f32_e32 v3, v135, v0
	v_mul_f32_e32 v3, 0x3fb8aa3b, v3
	v_exp_f32_e32 v38, v3
	v_sub_f32_e32 v3, v133, v0
	v_mul_f32_e32 v3, 0x3fb8aa3b, v3
	v_exp_f32_e32 v39, v3
	v_sub_f32_e32 v3, v131, v0
	v_mul_f32_e32 v3, 0x3fb8aa3b, v3
	v_exp_f32_e32 v88, v3
	v_sub_f32_e32 v3, v122, v0
	v_mul_f32_e32 v3, 0x3fb8aa3b, v3
	v_exp_f32_e32 v90, v3
	v_sub_f32_e32 v3, v86, v0
	v_mul_f32_e32 v3, 0x3fb8aa3b, v3
	v_exp_f32_e32 v86, v3
	v_sub_f32_e32 v3, v84, v0
	v_mul_f32_e32 v3, 0x3fb8aa3b, v3
	v_exp_f32_e32 v84, v3
	v_sub_f32_e32 v3, v82, v0
	v_mul_f32_e32 v3, 0x3fb8aa3b, v3
	v_exp_f32_e32 v82, v3
	v_sub_f32_e32 v3, v80, v0
	v_mul_f32_e32 v3, 0x3fb8aa3b, v3
	v_exp_f32_e32 v80, v3
	v_sub_f32_e32 v3, v78, v0
	v_mul_f32_e32 v3, 0x3fb8aa3b, v3
	v_exp_f32_e32 v78, v3
	v_sub_f32_e32 v3, v21, v0
	v_mul_f32_e32 v3, 0x3fb8aa3b, v3
	v_exp_f32_e32 v21, v3
	v_sub_f32_e32 v3, v20, v0
	v_mul_f32_e32 v3, 0x3fb8aa3b, v3
	v_exp_f32_e32 v20, v3
	v_sub_f32_e32 v3, v19, v0
	v_mul_f32_e32 v3, 0x3fb8aa3b, v3
	v_exp_f32_e32 v92, v3
	v_sub_f32_e32 v3, v18, v0
	v_mul_f32_e32 v3, 0x3fb8aa3b, v3
	v_exp_f32_e32 v94, v3
	v_sub_f32_e32 v3, v17, v0
	v_sub_f32_e32 v2, v127, v0
; __device__ __forceinline__ unsigned cvt_pk_bf16(float lo, float hi) { const f32x2_cv v = {lo, hi}; return __builtin_bit_cast(unsigned, __builtin_convertvector(v, bf16x2_cv)); }
; #define LAS __attribute__((address_space(3)))
; __device__ __forceinline__ void attn_item(const bf16_t* Z, const float* ck, const float* cv, const float* btab, const float* sinks, bf16_t* MIX, int item, LAS unsigned char* lds, int tid, int wave, int lane) {
;     ...
; #pragma unroll
;         for (int mb = 0; mb < 12; ++mb)
; #pragma unroll
;             for (int i = 0; i < 4; ++i) { const float e = __expf(sacc[mb][nb][i] - mx); sum += e; sacc[mb][nb][i] = e; }
;         sum += __shfl_xor(sum, 16); sum += __shfl_xor(sum, 32); sum += __expf(sink - mx);
;         inv[nb] = 1.0f / sum;
;     }
;     bf16x8 Pf[2][6];
; #pragma unroll
;     for (int nb = 0; nb < 2; ++nb)
; #pragma unroll
;         for (int ks = 0; ks < 6; ++ks) { u32x4 p; p.x = cvt_pk_bf16(sacc[2 * ks][nb][0], sacc[2 * ks][nb][1]); p.y = cvt_pk_bf16(sacc[2 * ks][nb][2], sacc[2 * ks][nb][3]);
;             p.z = cvt_pk_bf16(sacc[2 * ks + 1][nb][0], sacc[2 * ks + 1][nb][1]); p.w = cvt_pk_bf16(sacc[2 * ks + 1][nb][2], sacc[2 * ks + 1][nb][3]); Pf[nb][ks] = __builtin_bit_cast(bf16x8, p); }
; #pragma unroll
;     for (int db = 0; db < 8; ++db) {
;         f32x4 o0 = {0.f, 0.f, 0.f, 0.f}, o1 = {0.f, 0.f, 0.f, 0.f};
; #pragma unroll
;         for (int ks = 0; ks < 6; ++ks) { const LAS bf16_t* vp = VTs + (16 * db + c16) * VT_STRIDE + 32 * ks + 4 * g; const u32x2 lo = *(const LAS u32x2*)vp, hi = *(const LAS u32x2*)(vp + 16);
;             const bf16x8 Vf = __builtin_bit_cast(bf16x8, ((u32x4){lo.x, lo.y, hi.x, hi.y}));
;             o0 = __builtin_amdgcn_mfma_f32_16x16x32_bf16(Vf, Pf[0][ks], o0, 0, 0, 0);
;             o1 = __builtin_amdgcn_mfma_f32_16x16x32_bf16(Vf, Pf[1][ks], o1, 0, 0, 0); }
	v_mul_f32_e32 v3, 0x3fb8aa3b, v3
	v_mul_f32_e32 v2, 0x3fb8aa3b, v2
	v_exp_f32_e32 v96, v3
	v_sub_f32_e32 v3, v16, v0
	v_exp_f32_e32 v22, v2
	v_mul_f32_e32 v3, 0x3fb8aa3b, v3
	v_exp_f32_e32 v98, v3
	v_sub_f32_e32 v3, v15, v0
	v_mul_f32_e32 v3, 0x3fb8aa3b, v3
	v_exp_f32_e32 v15, v3
	v_sub_f32_e32 v3, v14, v0
	v_add_f32_e32 v2, 0, v22
	v_mul_f32_e32 v3, 0x3fb8aa3b, v3
	v_add_f32_e32 v2, v23, v2
	v_exp_f32_e32 v14, v3
	v_sub_f32_e32 v3, v13, v0
	v_add_f32_e32 v2, v28, v2
	v_mul_f32_e32 v3, 0x3fb8aa3b, v3
	v_add_f32_e32 v2, v29, v2
	v_exp_f32_e32 v13, v3
	v_sub_f32_e32 v3, v12, v0
	v_add_f32_e32 v2, v30, v2
	v_mul_f32_e32 v3, 0x3fb8aa3b, v3
	v_add_f32_e32 v2, v31, v2
	v_exp_f32_e32 v12, v3
	v_sub_f32_e32 v3, v11, v0
	v_add_f32_e32 v2, v36, v2
	v_mul_f32_e32 v3, 0x3fb8aa3b, v3
	v_add_f32_e32 v2, v37, v2
	v_exp_f32_e32 v100, v3
	v_sub_f32_e32 v3, v10, v0
	v_add_f32_e32 v2, v38, v2
	v_mul_f32_e32 v3, 0x3fb8aa3b, v3
	v_add_f32_e32 v2, v39, v2
	v_exp_f32_e32 v122, v3
	v_sub_f32_e32 v3, v9, v0
	v_add_f32_e32 v2, v88, v2
	v_mul_f32_e32 v3, 0x3fb8aa3b, v3
	v_add_f32_e32 v2, v90, v2
	v_exp_f32_e32 v124, v3
	v_sub_f32_e32 v3, v8, v0
	v_add_f32_e32 v2, v86, v2
	v_mul_f32_e32 v3, 0x3fb8aa3b, v3
	v_add_f32_e32 v2, v84, v2
	v_exp_f32_e32 v125, v3
	v_sub_f32_e32 v3, v6, v0
	v_add_f32_e32 v2, v82, v2
	v_mul_f32_e32 v3, 0x3fb8aa3b, v3
	v_add_f32_e32 v2, v80, v2
	v_exp_f32_e32 v6, v3
	v_sub_f32_e32 v3, v76, v0
	v_add_f32_e32 v2, v78, v2
	v_mul_f32_e32 v3, 0x3fb8aa3b, v3
	v_add_f32_e32 v2, v21, v2
	v_exp_f32_e32 v76, v3
	v_sub_f32_e32 v3, v74, v0
	v_add_f32_e32 v2, v20, v2
	v_mul_f32_e32 v3, 0x3fb8aa3b, v3
	v_add_f32_e32 v2, v92, v2
	v_exp_f32_e32 v74, v3
	v_sub_f32_e32 v3, v72, v0
	v_add_f32_e32 v2, v94, v2
	v_mul_f32_e32 v3, 0x3fb8aa3b, v3
	v_add_f32_e32 v2, v96, v2
	v_exp_f32_e32 v72, v3
	v_sub_f32_e32 v3, v7, v0
	v_add_f32_e32 v2, v98, v2
	v_mul_f32_e32 v3, 0x3fb8aa3b, v3
	v_add_f32_e32 v2, v15, v2
	v_exp_f32_e32 v7, v3
	v_sub_f32_e32 v3, v70, v0
	v_add_f32_e32 v2, v14, v2
	v_mul_f32_e32 v3, 0x3fb8aa3b, v3
	v_add_f32_e32 v2, v13, v2
	v_exp_f32_e32 v70, v3
	v_sub_f32_e32 v3, v68, v0
	v_add_f32_e32 v2, v12, v2
	v_mul_f32_e32 v3, 0x3fb8aa3b, v3
	v_add_f32_e32 v2, v100, v2
	v_exp_f32_e32 v68, v3
	v_sub_f32_e32 v3, v66, v0
	v_add_f32_e32 v2, v122, v2
	v_mul_f32_e32 v3, 0x3fb8aa3b, v3
	v_add_f32_e32 v2, v124, v2
	v_exp_f32_e32 v66, v3
	v_sub_f32_e32 v3, v4, v0
	v_add_f32_e32 v2, v125, v2
	v_mul_f32_e32 v3, 0x3fb8aa3b, v3
	v_add_f32_e32 v2, v6, v2
	v_exp_f32_e32 v4, v3
	v_sub_f32_e32 v3, v64, v0
	v_add_f32_e32 v2, v76, v2
	v_mul_f32_e32 v3, 0x3fb8aa3b, v3
	v_add_f32_e32 v2, v74, v2
	v_exp_f32_e32 v64, v3
	v_sub_f32_e32 v3, v62, v0
	v_add_f32_e32 v2, v72, v2
	v_mul_f32_e32 v3, 0x3fb8aa3b, v3
	v_add_f32_e32 v2, v7, v2
	v_exp_f32_e32 v62, v3
	v_sub_f32_e32 v3, v60, v0
	v_add_f32_e32 v2, v70, v2
	v_mul_f32_e32 v3, 0x3fb8aa3b, v3
	v_add_f32_e32 v2, v68, v2
	v_exp_f32_e32 v60, v3
	v_sub_f32_e32 v3, v5, v0
	v_add_f32_e32 v2, v66, v2
	v_mul_f32_e32 v3, 0x3fb8aa3b, v3
	v_add_f32_e32 v2, v4, v2
	v_exp_f32_e32 v5, v3
	v_add_f32_e32 v2, v64, v2
	v_add_f32_e32 v2, v62, v2
	v_add_f32_e32 v2, v60, v2
	v_add_f32_e32 v2, v5, v2
	v_cvt_pk_bf16_f32 v5, v60, v5
	ds_read2_b64 v[58:61], v51 offset0:128 offset1:132
	v_sub_f32_e32 v3, v54, v0
	v_mul_f32_e32 v3, 0x3fb8aa3b, v3
	v_cvt_pk_bf16_f32 v45, v28, v29
	v_cvt_pk_bf16_f32 v46, v30, v31
	v_cvt_pk_bf16_f32 v29, v20, v92
	v_cvt_pk_bf16_f32 v31, v98, v15
	v_cvt_pk_bf16_f32 v20, v14, v13
	v_cvt_pk_bf16_f32 v14, v70, v68
	v_cvt_pk_bf16_f32 v15, v66, v4
	ds_read2_b64 v[66:69], v51 offset0:136 offset1:140
	v_exp_f32_e32 v54, v3
	v_sub_f32_e32 v3, v52, v0
	v_mul_f32_e32 v3, 0x3fb8aa3b, v3
	v_exp_f32_e32 v52, v3
	v_sub_f32_e32 v3, v50, v0
	v_mul_f32_e32 v3, 0x3fb8aa3b, v3
	v_sub_f32_e32 v1, v1, v0
	v_cvt_pk_bf16_f32 v44, v22, v23
	v_cvt_pk_bf16_f32 v47, v36, v37
	v_exp_f32_e32 v126, v3
	v_mul_f32_e32 v1, 0x3fb8aa3b, v1
	v_cvt_pk_bf16_f32 v4, v64, v62
	s_waitcnt lgkmcnt(1)
	v_mfma_f32_16x16x32_bf16 v[62:65], v[58:61], v[40:43], 0
	v_exp_f32_e32 v127, v1
	v_add_f32_e32 v2, v54, v2
	v_add_f32_e32 v2, v52, v2
	v_mfma_f32_16x16x32_bf16 v[58:61], v[58:61], v[44:47], 0
	v_cvt_pk_bf16_f32 v36, v38, v39
	v_cvt_pk_bf16_f32 v37, v88, v90
	v_cvt_pk_bf16_f32 v38, v86, v84
	v_cvt_pk_bf16_f32 v39, v82, v80
	v_add_f32_e32 v2, v126, v2
	s_waitcnt lgkmcnt(0)
	v_mfma_f32_16x16x32_bf16 v[62:65], v[66:69], v[32:35], v[62:65]
	v_add_f32_e32 v1, v127, v2
	ds_bpermute_b32 v2, v151, v1
	v_sub_f32_e32 v0, v150, v0
	v_mfma_f32_16x16x32_bf16 v[58:61], v[66:69], v[36:39], v[58:61]
	ds_read2_b64 v[66:69], v51 offset0:144 offset1:148
	v_cvt_pk_bf16_f32 v28, v78, v21
	s_waitcnt lgkmcnt(1)
	v_add_f32_e32 v1, v1, v2
	ds_bpermute_b32 v2, v152, v1
	v_cvt_pk_bf16_f32 v30, v94, v96
	v_mul_f32_e32 v0, 0x3fb8aa3b, v0
	s_waitcnt lgkmcnt(1)
	v_mfma_f32_16x16x32_bf16 v[62:65], v[66:69], v[24:27], v[62:65]
	v_exp_f32_e32 v0, v0
	s_waitcnt lgkmcnt(0)
	v_add_f32_e32 v1, v1, v2
	v_cvt_pk_bf16_f32 v16, v91, v95
	v_mfma_f32_16x16x32_bf16 v[58:61], v[66:69], v[28:31], v[58:61]
	ds_read2_b64 v[66:69], v51 offset0:152 offset1:156
	v_add_f32_e32 v0, v0, v1
	v_div_scale_f32 v1, s[6:7], v0, v0, 1.0
	v_rcp_f32_e32 v2, v1
	v_cvt_pk_bf16_f32 v17, v97, v99
	v_cvt_pk_bf16_f32 v18, v101, v102
	v_cvt_pk_bf16_f32 v19, v103, v104
	v_cvt_pk_bf16_f32 v21, v12, v100
	v_cvt_pk_bf16_f32 v22, v122, v124
	v_cvt_pk_bf16_f32 v23, v125, v6
	s_waitcnt lgkmcnt(0)
; __device__ __forceinline__ unsigned cvt_pk_bf16(float lo, float hi) { const f32x2_cv v = {lo, hi}; return __builtin_bit_cast(unsigned, __builtin_convertvector(v, bf16x2_cv)); }
; #define LAS __attribute__((address_space(3)))
; __device__ __forceinline__ void attn_item(const bf16_t* Z, const float* ck, const float* cv, const float* btab, const float* sinks, bf16_t* MIX, int item, LAS unsigned char* lds, int tid, int wave, int lane) {
;     ...
;     for (int db = 0; db < 8; ++db) {
;         f32x4 o0 = {0.f, 0.f, 0.f, 0.f}, o1 = {0.f, 0.f, 0.f, 0.f};
; #pragma unroll
;         for (int ks = 0; ks < 6; ++ks) { const LAS bf16_t* vp = VTs + (16 * db + c16) * VT_STRIDE + 32 * ks + 4 * g; const u32x2 lo = *(const LAS u32x2*)vp, hi = *(const LAS u32x2*)(vp + 16);
;             const bf16x8 Vf = __builtin_bit_cast(bf16x8, ((u32x4){lo.x, lo.y, hi.x, hi.y}));
;             o0 = __builtin_amdgcn_mfma_f32_16x16x32_bf16(Vf, Pf[0][ks], o0, 0, 0, 0);
;             o1 = __builtin_amdgcn_mfma_f32_16x16x32_bf16(Vf, Pf[1][ks], o1, 0, 0, 0); }
;         o0 = o0 * inv[0]; o1 = o1 * inv[1];
;         u32x2 w0, w1; w0.x = cvt_pk_bf16(o0[0], o0[1]); w0.y = cvt_pk_bf16(o0[2], o0[3]); w1.x = cvt_pk_bf16(o1[0], o1[1]); w1.y = cvt_pk_bf16(o1[2], o1[3]);
;         *(u32x2*)(MIX + (size_t)(qrow0 + qhalf * 32 + c16) * D + hq * 128 + 16 * db + 4 * g) = w0;
;         *(u32x2*)(MIX + (size_t)(qrow0 + qhalf * 32 + 16 + c16) * D + hq * 128 + 16 * db + 4 * g) = w1;
	v_mfma_f32_16x16x32_bf16 v[62:65], v[66:69], v[16:19], v[62:65]
	v_fma_f32 v3, -v1, v2, 1.0
	v_fmac_f32_e32 v2, v3, v2
	v_div_scale_f32 v3, vcc, 1.0, v0, 1.0
	v_mfma_f32_16x16x32_bf16 v[58:61], v[66:69], v[20:23], v[58:61]
	ds_read2_b64 v[66:69], v51 offset0:160 offset1:164
	v_mul_f32_e32 v8, v3, v2
	v_fma_f32 v9, -v1, v8, v3
	v_fmac_f32_e32 v8, v9, v2
	v_fma_f32 v1, -v1, v8, v3
	v_div_fmas_f32 v1, v1, v2, v8
	v_cvt_pk_bf16_f32 v8, v105, v106
	v_cvt_pk_bf16_f32 v9, v107, v108
	v_cvt_pk_bf16_f32 v10, v109, v110
	v_cvt_pk_bf16_f32 v11, v111, v112
	v_cvt_pk_bf16_f32 v12, v76, v74
	v_cvt_pk_bf16_f32 v13, v72, v7
	s_waitcnt lgkmcnt(0)
	v_mfma_f32_16x16x32_bf16 v[62:65], v[66:69], v[8:11], v[62:65]
	v_div_fixup_f32 v50, v1, v0, 1.0
	v_cvt_pk_bf16_f32 v0, v113, v114
	v_cvt_pk_bf16_f32 v1, v115, v116
	v_mfma_f32_16x16x32_bf16 v[58:61], v[66:69], v[12:15], v[58:61]
	ds_read2_b64 v[66:69], v51 offset0:168 offset1:172
	v_cvt_pk_bf16_f32 v2, v117, v118
	v_cvt_pk_bf16_f32 v3, v119, v123
	v_readlane_b32 s6, v236, 36
	v_readlane_b32 s7, v236, 54
	v_cvt_pk_bf16_f32 v6, v54, v52
	v_cvt_pk_bf16_f32 v7, v126, v127
	s_add_i32 s6, s7, s6
	s_waitcnt lgkmcnt(0)
	v_mfma_f32_16x16x32_bf16 v[62:65], v[66:69], v[0:3], v[62:65]
	v_add_u32_e32 v54, s6, v149
	v_lshlrev_b64 v[52:53], 12, v[54:55]
	v_add_u32_e32 v54, 16, v54
	v_mfma_f32_16x16x32_bf16 v[58:61], v[66:69], v[4:7], v[58:61]
	v_lshl_add_u64 v[52:53], s[70:71], 0, v[52:53]
	v_lshlrev_b64 v[54:55], 12, v[54:55]
	v_lshl_add_u64 v[52:53], v[52:53], 0, s[76:77]
	v_lshl_add_u64 v[54:55], s[70:71], 0, v[54:55]
	v_pk_mul_f32 v[64:65], v[48:49], v[64:65] op_sel_hi:[0,1]
	v_pk_mul_f32 v[62:63], v[48:49], v[62:63] op_sel_hi:[0,1]
	v_lshl_add_u64 v[52:53], v[52:53], 0, v[120:121]
	v_lshl_add_u64 v[54:55], v[54:55], 0, s[76:77]
	v_pk_mul_f32 v[60:61], v[60:61], v[50:51] op_sel_hi:[1,0]
	v_pk_mul_f32 v[58:59], v[58:59], v[50:51] op_sel_hi:[1,0]
	v_cvt_pk_bf16_f32 v62, v62, v63
	v_cvt_pk_bf16_f32 v63, v64, v65
	v_lshl_add_u64 v[54:55], v[54:55], 0, v[120:121]
	v_cvt_pk_bf16_f32 v58, v58, v59
	v_cvt_pk_bf16_f32 v59, v60, v61
	global_store_dwordx2 v[52:53], v[62:63], off
	global_store_dwordx2 v[54:55], v[58:59], off
	v_add_u32_e32 v51, 0xe000, v49
	ds_read2_b64 v[58:61], v51 offset0:144 offset1:148
	ds_read2_b64 v[66:69], v51 offset0:152 offset1:156
	s_waitcnt lgkmcnt(1)
	v_mfma_f32_16x16x32_bf16 v[62:65], v[58:61], v[40:43], 0
	v_mfma_f32_16x16x32_bf16 v[58:61], v[58:61], v[44:47], 0
	s_waitcnt lgkmcnt(0)
	v_mfma_f32_16x16x32_bf16 v[62:65], v[66:69], v[32:35], v[62:65]
	v_mfma_f32_16x16x32_bf16 v[58:61], v[66:69], v[36:39], v[58:61]
	ds_read2_b64 v[66:69], v51 offset0:160 offset1:164
	s_waitcnt lgkmcnt(0)
	v_mfma_f32_16x16x32_bf16 v[62:65], v[66:69], v[24:27], v[62:65]
	v_mfma_f32_16x16x32_bf16 v[58:61], v[66:69], v[28:31], v[58:61]
	ds_read2_b64 v[66:69], v51 offset0:168 offset1:172
	s_waitcnt lgkmcnt(0)
	v_mfma_f32_16x16x32_bf16 v[62:65], v[66:69], v[16:19], v[62:65]
	v_mfma_f32_16x16x32_bf16 v[58:61], v[66:69], v[20:23], v[58:61]
	ds_read2_b64 v[66:69], v51 offset0:176 offset1:180
	s_waitcnt lgkmcnt(0)
	v_mfma_f32_16x16x32_bf16 v[62:65], v[66:69], v[8:11], v[62:65]
	v_mfma_f32_16x16x32_bf16 v[58:61], v[66:69], v[12:15], v[58:61]
	ds_read2_b64 v[66:69], v51 offset0:184 offset1:188
	s_waitcnt lgkmcnt(0)
	v_mfma_f32_16x16x32_bf16 v[62:65], v[66:69], v[0:3], v[62:65]
	s_nop 7
	v_pk_mul_f32 v[64:65], v[48:49], v[64:65] op_sel_hi:[0,1]
	v_mfma_f32_16x16x32_bf16 v[58:61], v[66:69], v[4:7], v[58:61]
	v_mul_f32_e64 v62, v48, v62
	v_mul_f32_e64 v63, v48, v63
	v_cvt_pk_bf16_f32 v62, v62, v63
	v_cvt_pk_bf16_f32 v63, v64, v65
	v_add_u32_e32 v49, 0xf800, v49
	s_nop 2
	v_pk_mul_f32 v[60:61], v[60:61], v[50:51] op_sel_hi:[1,0]
	v_pk_mul_f32 v[58:59], v[58:59], v[50:51] op_sel_hi:[1,0]
	s_nop 0
	v_cvt_pk_bf16_f32 v58, v58, v59
	v_cvt_pk_bf16_f32 v59, v60, v61
	global_store_dwordx2 v[52:53], v[62:63], off offset:32
	global_store_dwordx2 v[54:55], v[58:59], off offset:32
	ds_read2_b64 v[58:61], v49 offset0:160 offset1:164
	ds_read2_b64 v[66:69], v49 offset0:168 offset1:172
	s_waitcnt lgkmcnt(1)
	v_mfma_f32_16x16x32_bf16 v[62:65], v[58:61], v[40:43], 0
	v_mfma_f32_16x16x32_bf16 v[58:61], v[58:61], v[44:47], 0
	s_waitcnt lgkmcnt(0)
	v_mfma_f32_16x16x32_bf16 v[62:65], v[66:69], v[32:35], v[62:65]
	v_mfma_f32_16x16x32_bf16 v[58:61], v[66:69], v[36:39], v[58:61]
	ds_read2_b64 v[66:69], v49 offset0:176 offset1:180
	s_waitcnt lgkmcnt(0)
	v_mfma_f32_16x16x32_bf16 v[62:65], v[66:69], v[24:27], v[62:65]
	v_mfma_f32_16x16x32_bf16 v[58:61], v[66:69], v[28:31], v[58:61]
	ds_read2_b64 v[66:69], v49 offset0:184 offset1:188
	s_waitcnt lgkmcnt(0)
	v_mfma_f32_16x16x32_bf16 v[62:65], v[66:69], v[16:19], v[62:65]
	v_mfma_f32_16x16x32_bf16 v[58:61], v[66:69], v[20:23], v[58:61]
	ds_read2_b64 v[66:69], v49 offset0:192 offset1:196
	s_waitcnt lgkmcnt(0)
	v_mfma_f32_16x16x32_bf16 v[62:65], v[66:69], v[8:11], v[62:65]
	v_mfma_f32_16x16x32_bf16 v[58:61], v[66:69], v[12:15], v[58:61]
	ds_read2_b64 v[66:69], v49 offset0:200 offset1:204
	s_waitcnt lgkmcnt(0)
	v_mfma_f32_16x16x32_bf16 v[62:65], v[66:69], v[0:3], v[62:65]
	s_nop 7
	v_pk_mul_f32 v[64:65], v[48:49], v[64:65] op_sel_hi:[0,1]
	v_mfma_f32_16x16x32_bf16 v[58:61], v[66:69], v[4:7], v[58:61]
	v_mul_f32_e64 v62, v48, v62
	v_mul_f32_e64 v63, v48, v63
	v_cvt_pk_bf16_f32 v62, v62, v63
	v_cvt_pk_bf16_f32 v63, v64, v65
	s_nop 3
	v_pk_mul_f32 v[60:61], v[50:51], v[60:61] op_sel_hi:[0,1]
	v_pk_mul_f32 v[58:59], v[50:51], v[58:59] op_sel_hi:[0,1]
	v_cvt_pk_bf16_f32 v58, v58, v59
	v_cvt_pk_bf16_f32 v59, v60, v61
	global_store_dwordx2 v[52:53], v[62:63], off offset:64
	global_store_dwordx2 v[54:55], v[58:59], off offset:64
	v_mad_u64_u32 v[58:59], s[6:7], v148, s8, v[56:57]
	v_add_u32_e32 v49, 0xc800, v58
	ds_read2_b64 v[58:61], v49 offset0:128 offset1:132
	ds_read2_b64 v[66:69], v49 offset0:136 offset1:140
	s_waitcnt lgkmcnt(1)
; __device__ __forceinline__ unsigned cvt_pk_bf16(float lo, float hi) { const f32x2_cv v = {lo, hi}; return __builtin_bit_cast(unsigned, __builtin_convertvector(v, bf16x2_cv)); }
; #define LAS __attribute__((address_space(3)))
; __device__ __forceinline__ void attn_item(const bf16_t* Z, const float* ck, const float* cv, const float* btab, const float* sinks, bf16_t* MIX, int item, LAS unsigned char* lds, int tid, int wave, int lane) {
;     ...
;     for (int db = 0; db < 8; ++db) {
;         f32x4 o0 = {0.f, 0.f, 0.f, 0.f}, o1 = {0.f, 0.f, 0.f, 0.f};
; #pragma unroll
;         for (int ks = 0; ks < 6; ++ks) { const LAS bf16_t* vp = VTs + (16 * db + c16) * VT_STRIDE + 32 * ks + 4 * g; const u32x2 lo = *(const LAS u32x2*)vp, hi = *(const LAS u32x2*)(vp + 16);
;             const bf16x8 Vf = __builtin_bit_cast(bf16x8, ((u32x4){lo.x, lo.y, hi.x, hi.y}));
;             o0 = __builtin_amdgcn_mfma_f32_16x16x32_bf16(Vf, Pf[0][ks], o0, 0, 0, 0);
;             o1 = __builtin_amdgcn_mfma_f32_16x16x32_bf16(Vf, Pf[1][ks], o1, 0, 0, 0); }
;         o0 = o0 * inv[0]; o1 = o1 * inv[1];
;         u32x2 w0, w1; w0.x = cvt_pk_bf16(o0[0], o0[1]); w0.y = cvt_pk_bf16(o0[2], o0[3]); w1.x = cvt_pk_bf16(o1[0], o1[1]); w1.y = cvt_pk_bf16(o1[2], o1[3]);
;         *(u32x2*)(MIX + (size_t)(qrow0 + qhalf * 32 + c16) * D + hq * 128 + 16 * db + 4 * g) = w0;
;         *(u32x2*)(MIX + (size_t)(qrow0 + qhalf * 32 + 16 + c16) * D + hq * 128 + 16 * db + 4 * g) = w1;
	v_mfma_f32_16x16x32_bf16 v[62:65], v[58:61], v[40:43], 0
	v_mfma_f32_16x16x32_bf16 v[58:61], v[58:61], v[44:47], 0
	s_waitcnt lgkmcnt(0)
	v_mfma_f32_16x16x32_bf16 v[62:65], v[66:69], v[32:35], v[62:65]
	v_mfma_f32_16x16x32_bf16 v[58:61], v[66:69], v[36:39], v[58:61]
	ds_read2_b64 v[66:69], v49 offset0:144 offset1:148
	s_waitcnt lgkmcnt(0)
	v_mfma_f32_16x16x32_bf16 v[62:65], v[66:69], v[24:27], v[62:65]
	v_mfma_f32_16x16x32_bf16 v[58:61], v[66:69], v[28:31], v[58:61]
	ds_read2_b64 v[66:69], v49 offset0:152 offset1:156
	s_waitcnt lgkmcnt(0)
	v_mfma_f32_16x16x32_bf16 v[62:65], v[66:69], v[16:19], v[62:65]
	v_mfma_f32_16x16x32_bf16 v[58:61], v[66:69], v[20:23], v[58:61]
	ds_read2_b64 v[66:69], v49 offset0:160 offset1:164
	s_waitcnt lgkmcnt(0)
	v_mfma_f32_16x16x32_bf16 v[62:65], v[66:69], v[8:11], v[62:65]
	v_mfma_f32_16x16x32_bf16 v[58:61], v[66:69], v[12:15], v[58:61]
	ds_read2_b64 v[66:69], v49 offset0:168 offset1:172
	s_waitcnt lgkmcnt(0)
	v_mfma_f32_16x16x32_bf16 v[62:65], v[66:69], v[0:3], v[62:65]
	s_nop 7
	v_pk_mul_f32 v[64:65], v[48:49], v[64:65] op_sel_hi:[0,1]
	v_mfma_f32_16x16x32_bf16 v[58:61], v[66:69], v[4:7], v[58:61]
	v_mul_f32_e64 v62, v48, v62
	v_mul_f32_e64 v63, v48, v63
	v_cvt_pk_bf16_f32 v62, v62, v63
	v_cvt_pk_bf16_f32 v63, v64, v65
	v_mad_u32_u24 v49, v147, s8, v56
	v_mad_u64_u32 v[56:57], s[6:7], v146, s8, v[56:57]
	s_nop 1
	v_pk_mul_f32 v[60:61], v[50:51], v[60:61] op_sel_hi:[0,1]
	v_pk_mul_f32 v[58:59], v[50:51], v[58:59] op_sel_hi:[0,1]
	v_cvt_pk_bf16_f32 v58, v58, v59
	v_cvt_pk_bf16_f32 v59, v60, v61
	global_store_dwordx2 v[52:53], v[62:63], off offset:96
	global_store_dwordx2 v[54:55], v[58:59], off offset:96
	v_add_u32_e32 v51, 0xc800, v49
	ds_read2_b64 v[58:61], v51 offset0:128 offset1:132
	ds_read2_b64 v[66:69], v51 offset0:136 offset1:140
	s_waitcnt lgkmcnt(1)
	v_mfma_f32_16x16x32_bf16 v[62:65], v[58:61], v[40:43], 0
	v_mfma_f32_16x16x32_bf16 v[58:61], v[58:61], v[44:47], 0
	s_waitcnt lgkmcnt(0)
	v_mfma_f32_16x16x32_bf16 v[62:65], v[66:69], v[32:35], v[62:65]
	v_mfma_f32_16x16x32_bf16 v[58:61], v[66:69], v[36:39], v[58:61]
	ds_read2_b64 v[66:69], v51 offset0:144 offset1:148
	s_waitcnt lgkmcnt(0)
	v_mfma_f32_16x16x32_bf16 v[62:65], v[66:69], v[24:27], v[62:65]
	v_mfma_f32_16x16x32_bf16 v[58:61], v[66:69], v[28:31], v[58:61]
	ds_read2_b64 v[66:69], v51 offset0:152 offset1:156
	s_waitcnt lgkmcnt(0)
	v_mfma_f32_16x16x32_bf16 v[62:65], v[66:69], v[16:19], v[62:65]
	v_mfma_f32_16x16x32_bf16 v[58:61], v[66:69], v[20:23], v[58:61]
	ds_read2_b64 v[66:69], v51 offset0:160 offset1:164
	s_waitcnt lgkmcnt(0)
	v_mfma_f32_16x16x32_bf16 v[62:65], v[66:69], v[8:11], v[62:65]
	v_mfma_f32_16x16x32_bf16 v[58:61], v[66:69], v[12:15], v[58:61]
	ds_read2_b64 v[66:69], v51 offset0:168 offset1:172
	s_waitcnt lgkmcnt(0)
	v_mfma_f32_16x16x32_bf16 v[62:65], v[66:69], v[0:3], v[62:65]
	s_nop 7
	v_pk_mul_f32 v[64:65], v[48:49], v[64:65] op_sel_hi:[0,1]
	v_mfma_f32_16x16x32_bf16 v[58:61], v[66:69], v[4:7], v[58:61]
	v_mul_f32_e64 v62, v48, v62
	v_mul_f32_e64 v63, v48, v63
	v_cvt_pk_bf16_f32 v62, v62, v63
	v_cvt_pk_bf16_f32 v63, v64, v65
	s_nop 3
	v_pk_mul_f32 v[60:61], v[50:51], v[60:61] op_sel_hi:[0,1]
	v_pk_mul_f32 v[58:59], v[50:51], v[58:59] op_sel_hi:[0,1]
	v_cvt_pk_bf16_f32 v58, v58, v59
	v_cvt_pk_bf16_f32 v59, v60, v61
	global_store_dwordx2 v[52:53], v[62:63], off offset:128
	global_store_dwordx2 v[54:55], v[58:59], off offset:128
	v_add_u32_e32 v51, 0xe000, v49
	ds_read2_b64 v[58:61], v51 offset0:144 offset1:148
	ds_read2_b64 v[66:69], v51 offset0:152 offset1:156
	s_waitcnt lgkmcnt(1)
	v_mfma_f32_16x16x32_bf16 v[62:65], v[58:61], v[40:43], 0
	v_mfma_f32_16x16x32_bf16 v[58:61], v[58:61], v[44:47], 0
	s_waitcnt lgkmcnt(0)
	v_mfma_f32_16x16x32_bf16 v[62:65], v[66:69], v[32:35], v[62:65]
	v_mfma_f32_16x16x32_bf16 v[58:61], v[66:69], v[36:39], v[58:61]
	ds_read2_b64 v[66:69], v51 offset0:160 offset1:164
	s_waitcnt lgkmcnt(0)
	v_mfma_f32_16x16x32_bf16 v[62:65], v[66:69], v[24:27], v[62:65]
	v_mfma_f32_16x16x32_bf16 v[58:61], v[66:69], v[28:31], v[58:61]
	ds_read2_b64 v[66:69], v51 offset0:168 offset1:172
	s_waitcnt lgkmcnt(0)
	v_mfma_f32_16x16x32_bf16 v[62:65], v[66:69], v[16:19], v[62:65]
	v_mfma_f32_16x16x32_bf16 v[58:61], v[66:69], v[20:23], v[58:61]
	ds_read2_b64 v[66:69], v51 offset0:176 offset1:180
	s_waitcnt lgkmcnt(0)
; __device__ __forceinline__ unsigned cvt_pk_bf16(float lo, float hi) { const f32x2_cv v = {lo, hi}; return __builtin_bit_cast(unsigned, __builtin_convertvector(v, bf16x2_cv)); }
; #define LAS __attribute__((address_space(3)))
; __device__ __forceinline__ void attn_item(const bf16_t* Z, const float* ck, const float* cv, const float* btab, const float* sinks, bf16_t* MIX, int item, LAS unsigned char* lds, int tid, int wave, int lane) {
;     ...
;     for (int db = 0; db < 8; ++db) {
;         f32x4 o0 = {0.f, 0.f, 0.f, 0.f}, o1 = {0.f, 0.f, 0.f, 0.f};
; #pragma unroll
;         for (int ks = 0; ks < 6; ++ks) { const LAS bf16_t* vp = VTs + (16 * db + c16) * VT_STRIDE + 32 * ks + 4 * g; const u32x2 lo = *(const LAS u32x2*)vp, hi = *(const LAS u32x2*)(vp + 16);
;             const bf16x8 Vf = __builtin_bit_cast(bf16x8, ((u32x4){lo.x, lo.y, hi.x, hi.y}));
;             o0 = __builtin_amdgcn_mfma_f32_16x16x32_bf16(Vf, Pf[0][ks], o0, 0, 0, 0);
;             o1 = __builtin_amdgcn_mfma_f32_16x16x32_bf16(Vf, Pf[1][ks], o1, 0, 0, 0); }
;         o0 = o0 * inv[0]; o1 = o1 * inv[1];
;         u32x2 w0, w1; w0.x = cvt_pk_bf16(o0[0], o0[1]); w0.y = cvt_pk_bf16(o0[2], o0[3]); w1.x = cvt_pk_bf16(o1[0], o1[1]); w1.y = cvt_pk_bf16(o1[2], o1[3]);
;         *(u32x2*)(MIX + (size_t)(qrow0 + qhalf * 32 + c16) * D + hq * 128 + 16 * db + 4 * g) = w0;
;         *(u32x2*)(MIX + (size_t)(qrow0 + qhalf * 32 + 16 + c16) * D + hq * 128 + 16 * db + 4 * g) = w1;
;     }
;     __syncthreads();
	v_mfma_f32_16x16x32_bf16 v[62:65], v[66:69], v[8:11], v[62:65]
	v_mfma_f32_16x16x32_bf16 v[58:61], v[66:69], v[12:15], v[58:61]
	ds_read2_b64 v[66:69], v51 offset0:184 offset1:188
	s_waitcnt lgkmcnt(0)
	v_mfma_f32_16x16x32_bf16 v[62:65], v[66:69], v[0:3], v[62:65]
	s_nop 7
	v_pk_mul_f32 v[64:65], v[48:49], v[64:65] op_sel_hi:[0,1]
	v_mfma_f32_16x16x32_bf16 v[58:61], v[66:69], v[4:7], v[58:61]
	v_mul_f32_e64 v62, v48, v62
	v_mul_f32_e64 v63, v48, v63
	v_cvt_pk_bf16_f32 v62, v62, v63
	v_cvt_pk_bf16_f32 v63, v64, v65
	v_add_u32_e32 v49, 0xf800, v49
	s_nop 2
	v_pk_mul_f32 v[60:61], v[50:51], v[60:61] op_sel_hi:[0,1]
	v_pk_mul_f32 v[58:59], v[50:51], v[58:59] op_sel_hi:[0,1]
	v_cvt_pk_bf16_f32 v58, v58, v59
	v_cvt_pk_bf16_f32 v59, v60, v61
	global_store_dwordx2 v[52:53], v[62:63], off offset:160
	global_store_dwordx2 v[54:55], v[58:59], off offset:160
	ds_read2_b64 v[58:61], v49 offset0:160 offset1:164
	ds_read2_b64 v[66:69], v49 offset0:168 offset1:172
	s_waitcnt lgkmcnt(1)
	v_mfma_f32_16x16x32_bf16 v[62:65], v[58:61], v[40:43], 0
	v_mfma_f32_16x16x32_bf16 v[58:61], v[58:61], v[44:47], 0
	s_waitcnt lgkmcnt(0)
	v_mfma_f32_16x16x32_bf16 v[62:65], v[66:69], v[32:35], v[62:65]
	v_mfma_f32_16x16x32_bf16 v[58:61], v[66:69], v[36:39], v[58:61]
	ds_read2_b64 v[66:69], v49 offset0:176 offset1:180
	s_waitcnt lgkmcnt(0)
	v_mfma_f32_16x16x32_bf16 v[62:65], v[66:69], v[24:27], v[62:65]
	v_mfma_f32_16x16x32_bf16 v[58:61], v[66:69], v[28:31], v[58:61]
	ds_read2_b64 v[66:69], v49 offset0:184 offset1:188
	s_waitcnt lgkmcnt(0)
	v_mfma_f32_16x16x32_bf16 v[62:65], v[66:69], v[16:19], v[62:65]
	v_mfma_f32_16x16x32_bf16 v[58:61], v[66:69], v[20:23], v[58:61]
	ds_read2_b64 v[66:69], v49 offset0:192 offset1:196
	s_waitcnt lgkmcnt(0)
	v_mfma_f32_16x16x32_bf16 v[62:65], v[66:69], v[8:11], v[62:65]
	v_mfma_f32_16x16x32_bf16 v[58:61], v[66:69], v[12:15], v[58:61]
	ds_read2_b64 v[66:69], v49 offset0:200 offset1:204
	s_waitcnt lgkmcnt(0)
	v_mfma_f32_16x16x32_bf16 v[62:65], v[66:69], v[0:3], v[62:65]
	s_nop 7
	v_pk_mul_f32 v[64:65], v[48:49], v[64:65] op_sel_hi:[0,1]
	v_mfma_f32_16x16x32_bf16 v[58:61], v[66:69], v[4:7], v[58:61]
	v_mul_f32_e64 v62, v48, v62
	v_mul_f32_e64 v63, v48, v63
	v_cvt_pk_bf16_f32 v62, v62, v63
	v_cvt_pk_bf16_f32 v63, v64, v65
	v_add_u32_e32 v49, 0xc800, v56
	s_nop 2
	v_pk_mul_f32 v[60:61], v[50:51], v[60:61] op_sel_hi:[0,1]
	v_pk_mul_f32 v[58:59], v[50:51], v[58:59] op_sel_hi:[0,1]
	v_cvt_pk_bf16_f32 v58, v58, v59
	v_cvt_pk_bf16_f32 v59, v60, v61
	global_store_dwordx2 v[52:53], v[62:63], off offset:192
	global_store_dwordx2 v[54:55], v[58:59], off offset:192
	ds_read2_b64 v[56:59], v49 offset0:128 offset1:132
	s_waitcnt lgkmcnt(0)
	v_mfma_f32_16x16x32_bf16 v[40:43], v[56:59], v[40:43], 0
	v_mfma_f32_16x16x32_bf16 v[44:47], v[56:59], v[44:47], 0
	ds_read2_b64 v[56:59], v49 offset0:136 offset1:140
	s_waitcnt lgkmcnt(0)
	v_mfma_f32_16x16x32_bf16 v[32:35], v[56:59], v[32:35], v[40:43]
	s_nop 3
	ds_read2_b64 v[40:43], v49 offset0:144 offset1:148
	s_waitcnt lgkmcnt(0)
	v_mfma_f32_16x16x32_bf16 v[24:27], v[40:43], v[24:27], v[32:35]
	s_nop 2
	ds_read2_b64 v[32:35], v49 offset0:152 offset1:156
	s_waitcnt lgkmcnt(0)
	v_mfma_f32_16x16x32_bf16 v[16:19], v[32:35], v[16:19], v[24:27]
	s_nop 2
	ds_read2_b64 v[24:27], v49 offset0:160 offset1:164
	v_mfma_f32_16x16x32_bf16 v[36:39], v[56:59], v[36:39], v[44:47]
	v_mfma_f32_16x16x32_bf16 v[28:31], v[40:43], v[28:31], v[36:39]
	s_waitcnt lgkmcnt(0)
	v_mfma_f32_16x16x32_bf16 v[8:11], v[24:27], v[8:11], v[16:19]
	s_nop 2
	ds_read2_b64 v[16:19], v49 offset0:168 offset1:172
	v_mfma_f32_16x16x32_bf16 v[20:23], v[32:35], v[20:23], v[28:31]
	v_mfma_f32_16x16x32_bf16 v[12:15], v[24:27], v[12:15], v[20:23]
	s_waitcnt lgkmcnt(0)
	v_mfma_f32_16x16x32_bf16 v[0:3], v[16:19], v[0:3], v[8:11]
	v_mfma_f32_16x16x32_bf16 v[4:7], v[16:19], v[4:7], v[12:15]
	s_nop 6
	v_mul_f32_e64 v2, v48, v2
	v_mul_f32_e64 v3, v48, v3
	v_pk_mul_f32 v[0:1], v[48:49], v[0:1] op_sel_hi:[0,1]
	v_pk_mul_f32 v[6:7], v[50:51], v[6:7] op_sel_hi:[0,1]
	v_pk_mul_f32 v[4:5], v[50:51], v[4:5] op_sel_hi:[0,1]
	v_cvt_pk_bf16_f32 v0, v0, v1
	v_cvt_pk_bf16_f32 v1, v2, v3
	v_cvt_pk_bf16_f32 v2, v4, v5
	v_cvt_pk_bf16_f32 v3, v6, v7
	global_store_dwordx2 v[52:53], v[0:1], off offset:224
	global_store_dwordx2 v[54:55], v[2:3], off offset:224
	s_barrier
	s_cbranch_execnz .LBB0_504
	s_branch .LBB0_595
